# GU epilogue: gate rows requested four row groups ahead through spare registers
# speedup vs baseline: 1.0245x; 1.0030x over previous
; __device__ __forceinline__ f32x4 gelu4(const f32x4 x) { const f32x4 u = (x + x * x * x * 0.044715f) * 1.5957691216f; return x * sigmoid4(u); }
; __device__ __forceinline__ float bf_lo(unsigned w) { return __uint_as_float(w << 16); }
; __device__ __forceinline__ float bf_hi(unsigned w) { return __uint_as_float(w & 0xffff0000u); }
;     __device__ __forceinline__ void operator()(const f32x4 (&acc)[2][2][4][2], const pg8::Unit& u_in, int wr, int wc, int fr, int fq) const {
;     ...
;             bf16_t* o0 = (bf16_t*)(ws + OFF_R1); constexpr int ldc = 3072; const float* p0 = kp->in[13];
;             const int col0 = u.pn * 256 + wc * 32 + 8 * fq;
;             f32x4 bv[2][2];
; #pragma unroll
;             for (int bj = 0; bj < 2; ++bj)
; #pragma unroll
;                 for (int n = 0; n < 2; ++n) bv[bj][n] = *(const f32x4*)(p0 + col0 + bj * 128 + 4 * n);
;             u32x4 qc[2], qn[2];
;             qc[0] = *(const u32x4*)(o0 + (size_t)row0 * ldc + col0); qc[1] = *(const u32x4*)(o0 + (size_t)row0 * ldc + col0 + 128); qn[0] = qc[0]; qn[1] = qc[1];
; #pragma unroll
;             for (int ai = 0; ai < 2; ++ai)
; #pragma unroll
;                 for (int m = 0; m < 4; ++m) { bf16_t* rowp = o0 + (size_t)(row0 + ai * 128 + m * 16) * ldc + col0;
;                     if (ai * 4 + m < 7) { const int nx = ai * 4 + m + 1; const bf16_t* np = o0 + (size_t)(row0 + (nx >> 2) * 128 + (nx & 3) * 16) * ldc + col0; qn[0] = *(const u32x4*)np; qn[1] = *(const u32x4*)(np + 128); }
;                     asm volatile("" : "+v"(qc[0]), "+v"(qc[1]));
; #pragma unroll
;                     for (int bj = 0; bj < 2; ++bj) { f32x4 v0 = acc[ai][bj][m][0] + bv[bj][0], v1 = acc[ai][bj][m][1] + bv[bj][1];
;                         const u32x4 q = qc[bj];
;                         v0 = gelu4(v0) * (f32x4){bf_lo(q.x), bf_hi(q.x), bf_lo(q.y), bf_hi(q.y)}; v1 = gelu4(v1) * (f32x4){bf_lo(q.z), bf_hi(q.z), bf_lo(q.w), bf_hi(q.w)};
.LBB0_720:
	s_andn2_b64 vcc, exec, s[2:3]
	s_cbranch_vccnz .LBB0_722
	s_load_dwordx2 s[2:3], s[10:11], 0x68
	v_lshl_or_b32 v146, s63, 8, v212
	v_ashrrev_i32_e32 v147, 31, v146
	v_or_b32_e32 v0, 16, v180
	s_waitcnt lgkmcnt(0)
	v_lshl_add_u64 v[134:135], v[146:147], 2, s[2:3]
	global_load_dwordx4 v[138:141], v[134:135], off offset:16
	global_load_dwordx4 v[142:145], v[134:135], off
	global_load_dwordx4 v[130:133], v[134:135], off offset:528
	s_nop 0
	global_load_dwordx4 v[134:137], v[134:135], off offset:512
	s_add_u32 s2, s52, 0x3400000
	s_addc_u32 s3, s53, 0
	v_mov_b64_e32 v[148:149], s[2:3]
	v_mad_i64_i32 v[148:149], s[6:7], v180, s93, v[148:149]
	v_lshlrev_b64 v[146:147], 1, v[146:147]
	v_lshl_add_u64 v[148:149], v[148:149], 0, v[146:147]
	global_load_dwordx4 v[158:161], v[148:149], off
	global_load_dwordx4 v[154:157], v[148:149], off offset:256
	v_lshl_add_u64 v[182:183], s[2:3], 0, v[146:147]
	v_mad_i64_i32 v[162:163], s[2:3], v0, s93, v[182:183]
	global_load_dwordx4 v[150:153], v[162:163], off
	global_load_dwordx4 v[146:149], v[162:163], off offset:256
	v_add_u32_e32 v250, 0x20, v180
	v_mad_i64_i32 v[252:253], s[2:3], v250, s93, v[182:183]
	global_load_dwordx4 v[196:199], v[252:253], off
	global_load_dwordx4 v[200:203], v[252:253], off offset:256
	v_add_u32_e32 v250, 0x30, v180
	v_mad_i64_i32 v[252:253], s[2:3], v250, s93, v[182:183]
	global_load_dwordx4 v[204:207], v[252:253], off
	global_load_dwordx4 v[242:245], v[252:253], off offset:256
	v_mad_i64_i32 v[164:165], s[2:3], v180, s93, v[182:183]
	s_waitcnt vmcnt(4)
	v_pk_add_f32 v[186:187], v[126:127], v[142:143]
	v_pk_add_f32 v[184:185], v[128:129], v[144:145]
	v_pk_mul_f32 v[194:195], v[186:187], v[186:187]
	v_pk_mul_f32 v[192:193], v[184:185], v[184:185]
	v_pk_mul_f32 v[194:195], v[186:187], v[194:195]
	v_pk_mul_f32 v[192:193], v[184:185], v[192:193]
	v_pk_fma_f32 v[194:195], v[194:195], s[14:15], v[186:187] op_sel_hi:[1,0,1]
	v_pk_fma_f32 v[192:193], v[192:193], s[14:15], v[184:185] op_sel_hi:[1,0,1]
	v_pk_mul_f32 v[194:195], v[194:195], s[16:17] op_sel_hi:[1,0]
	v_pk_mul_f32 v[192:193], v[192:193], s[16:17] op_sel_hi:[1,0]
	v_mul_f32_e32 v0, 0xbfb8aa3b, v194
	v_exp_f32_e32 v0, v0
	v_pk_add_f32 v[190:191], v[122:123], v[138:139]
	v_pk_add_f32 v[188:189], v[124:125], v[140:141]
	v_add_f32_e32 v0, 1.0, v0
	v_rcp_f32_e32 v194, v0
	v_mul_f32_e32 v0, 0xbfb8aa3b, v195
	v_exp_f32_e32 v0, v0
	s_nop 0
	v_add_f32_e32 v0, 1.0, v0
	v_rcp_f32_e32 v195, v0
	v_mul_f32_e32 v0, 0xbfb8aa3b, v192
	v_exp_f32_e32 v0, v0
	v_pk_mul_f32 v[186:187], v[186:187], v[194:195]
	v_add_f32_e32 v0, 1.0, v0
	v_rcp_f32_e32 v192, v0
	v_mul_f32_e32 v0, 0xbfb8aa3b, v193
	v_exp_f32_e32 v0, v0
	s_nop 0
	v_add_f32_e32 v0, 1.0, v0
	v_rcp_f32_e32 v193, v0
	s_nop 0
	v_pk_mul_f32 v[184:185], v[184:185], v[192:193]
	v_lshlrev_b32_e32 v192, 16, v158
	v_and_b32_e32 v193, 0xffff0000, v158
	v_lshlrev_b32_e32 v158, 16, v159
	v_and_b32_e32 v159, 0xffff0000, v159
	v_pk_mul_f32 v[184:185], v[184:185], v[158:159]
	v_pk_mul_f32 v[158:159], v[186:187], v[192:193]
	v_pk_mul_f32 v[192:193], v[190:191], v[190:191]
	v_pk_mul_f32 v[186:187], v[188:189], v[188:189]
	v_pk_mul_f32 v[192:193], v[190:191], v[192:193]
	v_pk_mul_f32 v[186:187], v[188:189], v[186:187]
	v_pk_fma_f32 v[192:193], v[192:193], s[14:15], v[190:191] op_sel_hi:[1,0,1]
	v_pk_fma_f32 v[186:187], v[186:187], s[14:15], v[188:189] op_sel_hi:[1,0,1]
	v_pk_mul_f32 v[192:193], v[192:193], s[16:17] op_sel_hi:[1,0]
	v_pk_mul_f32 v[186:187], v[186:187], s[16:17] op_sel_hi:[1,0]
	v_mul_f32_e32 v0, 0xbfb8aa3b, v192
	v_exp_f32_e32 v0, v0
	v_cvt_pk_bf16_f32 v158, v158, v159
	v_cvt_pk_bf16_f32 v159, v184, v185
	v_pk_add_f32 v[184:185], v[114:115], v[134:135]
	v_add_f32_e32 v0, 1.0, v0
	v_rcp_f32_e32 v192, v0
	v_mul_f32_e32 v0, 0xbfb8aa3b, v193
	v_exp_f32_e32 v0, v0
	s_nop 0
	v_add_f32_e32 v0, 1.0, v0
	v_rcp_f32_e32 v193, v0
	v_mul_f32_e32 v0, 0xbfb8aa3b, v186
	v_exp_f32_e32 v0, v0
	s_nop 0
	v_add_f32_e32 v0, 1.0, v0
	v_rcp_f32_e32 v186, v0
	v_mul_f32_e32 v0, 0xbfb8aa3b, v187
	v_exp_f32_e32 v0, v0
	s_nop 0
	v_add_f32_e32 v0, 1.0, v0
	v_rcp_f32_e32 v187, v0
	s_nop 0
	v_pk_mul_f32 v[186:187], v[188:189], v[186:187]
	v_pk_mul_f32 v[188:189], v[190:191], v[192:193]
	v_lshlrev_b32_e32 v190, 16, v160
	v_and_b32_e32 v191, 0xffff0000, v160
	v_lshlrev_b32_e32 v160, 16, v161
	v_and_b32_e32 v161, 0xffff0000, v161
	v_pk_mul_f32 v[186:187], v[186:187], v[160:161]
	v_pk_mul_f32 v[160:161], v[188:189], v[190:191]
	v_pk_mul_f32 v[190:191], v[184:185], v[184:185]
	v_cvt_pk_bf16_f32 v160, v160, v161
	v_cvt_pk_bf16_f32 v161, v186, v187
	v_pk_add_f32 v[186:187], v[116:117], v[136:137]
	v_pk_mul_f32 v[190:191], v[184:185], v[190:191]
	v_pk_mul_f32 v[188:189], v[186:187], v[186:187]
	v_pk_fma_f32 v[190:191], v[190:191], s[14:15], v[184:185] op_sel_hi:[1,0,1]
	v_pk_mul_f32 v[188:189], v[186:187], v[188:189]
	v_pk_mul_f32 v[190:191], v[190:191], s[16:17] op_sel_hi:[1,0]
	v_pk_fma_f32 v[188:189], v[188:189], s[14:15], v[186:187] op_sel_hi:[1,0,1]
	v_mul_f32_e32 v0, 0xbfb8aa3b, v190
	v_exp_f32_e32 v0, v0
	v_pk_mul_f32 v[188:189], v[188:189], s[16:17] op_sel_hi:[1,0]
	global_store_dwordx4 v[164:165], v[158:161], off
	v_add_f32_e32 v0, 1.0, v0
	v_rcp_f32_e32 v190, v0
	v_mul_f32_e32 v0, 0xbfb8aa3b, v191
	v_exp_f32_e32 v0, v0
	v_pk_add_f32 v[158:159], v[106:107], v[130:131]
	v_pk_add_f32 v[160:161], v[108:109], v[132:133]
	v_add_f32_e32 v0, 1.0, v0
	v_rcp_f32_e32 v191, v0
	v_mul_f32_e32 v0, 0xbfb8aa3b, v188
	v_exp_f32_e32 v0, v0
	v_pk_mul_f32 v[184:185], v[184:185], v[190:191]
	v_pk_add_f32 v[190:191], v[110:111], v[138:139]
	v_add_f32_e32 v0, 1.0, v0
	v_rcp_f32_e32 v188, v0
	v_mul_f32_e32 v0, 0xbfb8aa3b, v189
; __device__ __forceinline__ f32x4 gelu4(const f32x4 x) { const f32x4 u = (x + x * x * x * 0.044715f) * 1.5957691216f; return x * sigmoid4(u); }
; __device__ __forceinline__ float bf_lo(unsigned w) { return __uint_as_float(w << 16); }
; __device__ __forceinline__ float bf_hi(unsigned w) { return __uint_as_float(w & 0xffff0000u); }
; __device__ __forceinline__ u32x4 pack8(const f32x4 a, const f32x4 b) { u32x4 w; w.x = cvt_pk_bf16(a[0], a[1]); w.y = cvt_pk_bf16(a[2], a[3]); w.z = cvt_pk_bf16(b[0], b[1]); w.w = cvt_pk_bf16(b[2], b[3]); return w; }
;     __device__ __forceinline__ void operator()(const f32x4 (&acc)[2][2][4][2], const pg8::Unit& u_in, int wr, int wc, int fr, int fq) const {
;     ...
;             for (int ai = 0; ai < 2; ++ai)
; #pragma unroll
;                 for (int m = 0; m < 4; ++m) { bf16_t* rowp = o0 + (size_t)(row0 + ai * 128 + m * 16) * ldc + col0;
;                     if (ai * 4 + m < 7) { const int nx = ai * 4 + m + 1; const bf16_t* np = o0 + (size_t)(row0 + (nx >> 2) * 128 + (nx & 3) * 16) * ldc + col0; qn[0] = *(const u32x4*)np; qn[1] = *(const u32x4*)(np + 128); }
;                     asm volatile("" : "+v"(qc[0]), "+v"(qc[1]));
; #pragma unroll
;                     for (int bj = 0; bj < 2; ++bj) { f32x4 v0 = acc[ai][bj][m][0] + bv[bj][0], v1 = acc[ai][bj][m][1] + bv[bj][1];
;                         const u32x4 q = qc[bj];
;                         v0 = gelu4(v0) * (f32x4){bf_lo(q.x), bf_hi(q.x), bf_lo(q.y), bf_hi(q.y)}; v1 = gelu4(v1) * (f32x4){bf_lo(q.z), bf_hi(q.z), bf_lo(q.w), bf_hi(q.w)};
;                         *(u32x4*)(rowp + bj * 128) = pack8(v0, v1); }
;                     qc[0] = qn[0]; qc[1] = qn[1]; }
	v_exp_f32_e32 v0, v0
	s_nop 0
	v_add_f32_e32 v0, 1.0, v0
	v_rcp_f32_e32 v189, v0
	s_nop 0
	v_pk_mul_f32 v[186:187], v[186:187], v[188:189]
	v_lshlrev_b32_e32 v188, 16, v154
	v_and_b32_e32 v189, 0xffff0000, v154
	v_lshlrev_b32_e32 v154, 16, v155
	v_and_b32_e32 v155, 0xffff0000, v155
	v_pk_mul_f32 v[186:187], v[186:187], v[154:155]
	v_pk_mul_f32 v[154:155], v[184:185], v[188:189]
	v_pk_mul_f32 v[188:189], v[158:159], v[158:159]
	v_pk_mul_f32 v[184:185], v[160:161], v[160:161]
	v_pk_mul_f32 v[188:189], v[158:159], v[188:189]
	v_pk_mul_f32 v[184:185], v[160:161], v[184:185]
	v_pk_fma_f32 v[188:189], v[188:189], s[14:15], v[158:159] op_sel_hi:[1,0,1]
	v_pk_fma_f32 v[184:185], v[184:185], s[14:15], v[160:161] op_sel_hi:[1,0,1]
	v_pk_mul_f32 v[188:189], v[188:189], s[16:17] op_sel_hi:[1,0]
	v_pk_mul_f32 v[184:185], v[184:185], s[16:17] op_sel_hi:[1,0]
	v_mul_f32_e32 v0, 0xbfb8aa3b, v188
	v_exp_f32_e32 v0, v0
	v_cvt_pk_bf16_f32 v154, v154, v155
	v_cvt_pk_bf16_f32 v155, v186, v187
	v_pk_add_f32 v[186:187], v[118:119], v[142:143]
	v_add_f32_e32 v0, 1.0, v0
	v_rcp_f32_e32 v188, v0
	v_mul_f32_e32 v0, 0xbfb8aa3b, v189
	v_exp_f32_e32 v0, v0
	v_pk_mul_f32 v[194:195], v[186:187], v[186:187]
	v_add_f32_e32 v0, 1.0, v0
	v_rcp_f32_e32 v189, v0
	v_mul_f32_e32 v0, 0xbfb8aa3b, v184
	v_exp_f32_e32 v0, v0
	v_pk_mul_f32 v[194:195], v[186:187], v[194:195]
	v_pk_mul_f32 v[158:159], v[158:159], v[188:189]
	v_pk_fma_f32 v[194:195], v[194:195], s[14:15], v[186:187] op_sel_hi:[1,0,1]
	v_add_f32_e32 v0, 1.0, v0
	v_rcp_f32_e32 v184, v0
	v_mul_f32_e32 v0, 0xbfb8aa3b, v185
	v_exp_f32_e32 v0, v0
	v_pk_mul_f32 v[194:195], v[194:195], s[16:17] op_sel_hi:[1,0]
	v_pk_add_f32 v[188:189], v[112:113], v[140:141]
	v_add_f32_e32 v0, 1.0, v0
	v_rcp_f32_e32 v185, v0
	v_or_b32_e32 v0, 32, v180
	v_pk_mul_f32 v[160:161], v[160:161], v[184:185]
	v_lshlrev_b32_e32 v184, 16, v156
	v_and_b32_e32 v185, 0xffff0000, v156
	v_lshlrev_b32_e32 v156, 16, v157
	v_and_b32_e32 v157, 0xffff0000, v157
	v_pk_mul_f32 v[160:161], v[160:161], v[156:157]
	v_pk_mul_f32 v[156:157], v[158:159], v[184:185]
	v_mad_i64_i32 v[184:185], s[2:3], v0, s93, v[182:183]
	v_mul_f32_e32 v0, 0xbfb8aa3b, v194
	v_exp_f32_e32 v0, v0
	v_cvt_pk_bf16_f32 v156, v156, v157
	v_cvt_pk_bf16_f32 v157, v160, v161
	global_store_dwordx4 v[164:165], v[154:157], off offset:256
	v_add_f32_e32 v0, 1.0, v0
	v_rcp_f32_e32 v194, v0
	v_mul_f32_e32 v0, 0xbfb8aa3b, v195
	v_pk_add_f32 v[164:165], v[120:121], v[144:145]
	v_exp_f32_e32 v0, v0
	v_pk_mul_f32 v[192:193], v[164:165], v[164:165]
	s_waitcnt vmcnt(4)
	v_add_u32_e32 v250, 0x80, v180
	v_mad_i64_i32 v[252:253], s[2:3], v250, s93, v[182:183]
	v_mov_b64_e32 v[158:159], v[196:197]
	v_mov_b64_e32 v[160:161], v[198:199]
	v_mov_b64_e32 v[154:155], v[200:201]
	v_mov_b64_e32 v[156:157], v[202:203]
	global_load_dwordx4 v[196:199], v[252:253], off
	global_load_dwordx4 v[200:203], v[252:253], off offset:256
	v_pk_mul_f32 v[192:193], v[164:165], v[192:193]
	v_add_f32_e32 v0, 1.0, v0
	v_pk_fma_f32 v[192:193], v[192:193], s[14:15], v[164:165] op_sel_hi:[1,0,1]
	v_rcp_f32_e32 v195, v0
	v_pk_mul_f32 v[192:193], v[192:193], s[16:17] op_sel_hi:[1,0]
	v_pk_mul_f32 v[186:187], v[186:187], v[194:195]
	v_mul_f32_e32 v0, 0xbfb8aa3b, v192
	v_exp_f32_e32 v0, v0
	s_nop 0
	v_add_f32_e32 v0, 1.0, v0
	v_rcp_f32_e32 v192, v0
	v_mul_f32_e32 v0, 0xbfb8aa3b, v193
	v_exp_f32_e32 v0, v0
	s_nop 0
	v_add_f32_e32 v0, 1.0, v0
	v_rcp_f32_e32 v193, v0
	s_nop 0
	v_pk_mul_f32 v[164:165], v[164:165], v[192:193]
	v_lshlrev_b32_e32 v192, 16, v150
	v_and_b32_e32 v193, 0xffff0000, v150
	v_lshlrev_b32_e32 v150, 16, v151
	v_and_b32_e32 v151, 0xffff0000, v151
	v_pk_mul_f32 v[164:165], v[164:165], v[150:151]
	v_pk_mul_f32 v[150:151], v[186:187], v[192:193]
	v_pk_mul_f32 v[192:193], v[190:191], v[190:191]
	v_pk_mul_f32 v[186:187], v[188:189], v[188:189]
	v_pk_mul_f32 v[192:193], v[190:191], v[192:193]
	v_pk_mul_f32 v[186:187], v[188:189], v[186:187]
	v_pk_fma_f32 v[192:193], v[192:193], s[14:15], v[190:191] op_sel_hi:[1,0,1]
	v_pk_fma_f32 v[186:187], v[186:187], s[14:15], v[188:189] op_sel_hi:[1,0,1]
	v_pk_mul_f32 v[192:193], v[192:193], s[16:17] op_sel_hi:[1,0]
	v_pk_mul_f32 v[186:187], v[186:187], s[16:17] op_sel_hi:[1,0]
	v_mul_f32_e32 v0, 0xbfb8aa3b, v192
	v_exp_f32_e32 v0, v0
	v_cvt_pk_bf16_f32 v150, v150, v151
	v_cvt_pk_bf16_f32 v151, v164, v165
	v_pk_add_f32 v[164:165], v[92:93], v[132:133]
	v_add_f32_e32 v0, 1.0, v0
	v_rcp_f32_e32 v192, v0
	v_mul_f32_e32 v0, 0xbfb8aa3b, v193
	v_exp_f32_e32 v0, v0
	s_nop 0
	v_add_f32_e32 v0, 1.0, v0
	v_rcp_f32_e32 v193, v0
	v_mul_f32_e32 v0, 0xbfb8aa3b, v186
	v_exp_f32_e32 v0, v0
	s_nop 0
	v_add_f32_e32 v0, 1.0, v0
	v_rcp_f32_e32 v186, v0
	v_mul_f32_e32 v0, 0xbfb8aa3b, v187
	v_exp_f32_e32 v0, v0
	s_nop 0
	v_add_f32_e32 v0, 1.0, v0
	v_rcp_f32_e32 v187, v0
	s_nop 0
	v_pk_mul_f32 v[186:187], v[188:189], v[186:187]
	v_pk_mul_f32 v[188:189], v[190:191], v[192:193]
	v_lshlrev_b32_e32 v190, 16, v152
	v_and_b32_e32 v191, 0xffff0000, v152
	v_lshlrev_b32_e32 v152, 16, v153
	v_and_b32_e32 v153, 0xffff0000, v153
	v_pk_mul_f32 v[186:187], v[186:187], v[152:153]
	v_pk_mul_f32 v[152:153], v[188:189], v[190:191]
	s_nop 0
	v_cvt_pk_bf16_f32 v152, v152, v153
	v_cvt_pk_bf16_f32 v153, v186, v187
	global_store_dwordx4 v[162:163], v[150:153], off
	v_pk_add_f32 v[186:187], v[90:91], v[130:131]
	s_nop 0
	v_pk_add_f32 v[152:153], v[98:99], v[134:135]
	v_pk_add_f32 v[150:151], v[100:101], v[136:137]
	v_pk_mul_f32 v[190:191], v[152:153], v[152:153]
	v_pk_mul_f32 v[188:189], v[150:151], v[150:151]
	v_pk_mul_f32 v[190:191], v[152:153], v[190:191]
	v_pk_mul_f32 v[188:189], v[150:151], v[188:189]
; __device__ __forceinline__ f32x4 gelu4(const f32x4 x) { const f32x4 u = (x + x * x * x * 0.044715f) * 1.5957691216f; return x * sigmoid4(u); }
; __device__ __forceinline__ float bf_lo(unsigned w) { return __uint_as_float(w << 16); }
; __device__ __forceinline__ float bf_hi(unsigned w) { return __uint_as_float(w & 0xffff0000u); }
; __device__ __forceinline__ u32x4 pack8(const f32x4 a, const f32x4 b) { u32x4 w; w.x = cvt_pk_bf16(a[0], a[1]); w.y = cvt_pk_bf16(a[2], a[3]); w.z = cvt_pk_bf16(b[0], b[1]); w.w = cvt_pk_bf16(b[2], b[3]); return w; }
;     __device__ __forceinline__ void operator()(const f32x4 (&acc)[2][2][4][2], const pg8::Unit& u_in, int wr, int wc, int fr, int fq) const {
;     ...
;             for (int ai = 0; ai < 2; ++ai)
; #pragma unroll
;                 for (int m = 0; m < 4; ++m) { bf16_t* rowp = o0 + (size_t)(row0 + ai * 128 + m * 16) * ldc + col0;
;                     if (ai * 4 + m < 7) { const int nx = ai * 4 + m + 1; const bf16_t* np = o0 + (size_t)(row0 + (nx >> 2) * 128 + (nx & 3) * 16) * ldc + col0; qn[0] = *(const u32x4*)np; qn[1] = *(const u32x4*)(np + 128); }
;                     asm volatile("" : "+v"(qc[0]), "+v"(qc[1]));
; #pragma unroll
;                     for (int bj = 0; bj < 2; ++bj) { f32x4 v0 = acc[ai][bj][m][0] + bv[bj][0], v1 = acc[ai][bj][m][1] + bv[bj][1];
;                         const u32x4 q = qc[bj];
;                         v0 = gelu4(v0) * (f32x4){bf_lo(q.x), bf_hi(q.x), bf_lo(q.y), bf_hi(q.y)}; v1 = gelu4(v1) * (f32x4){bf_lo(q.z), bf_hi(q.z), bf_lo(q.w), bf_hi(q.w)};
;                         *(u32x4*)(rowp + bj * 128) = pack8(v0, v1); }
;                     qc[0] = qn[0]; qc[1] = qn[1]; }
	v_pk_fma_f32 v[190:191], v[190:191], s[14:15], v[152:153] op_sel_hi:[1,0,1]
	v_pk_fma_f32 v[188:189], v[188:189], s[14:15], v[150:151] op_sel_hi:[1,0,1]
	v_pk_mul_f32 v[190:191], v[190:191], s[16:17] op_sel_hi:[1,0]
	v_pk_mul_f32 v[188:189], v[188:189], s[16:17] op_sel_hi:[1,0]
	v_mul_f32_e32 v0, 0xbfb8aa3b, v190
	v_exp_f32_e32 v0, v0
	s_nop 0
	v_add_f32_e32 v0, 1.0, v0
	v_rcp_f32_e32 v190, v0
	v_mul_f32_e32 v0, 0xbfb8aa3b, v191
	v_exp_f32_e32 v0, v0
	s_nop 0
	v_add_f32_e32 v0, 1.0, v0
	v_rcp_f32_e32 v191, v0
	v_mul_f32_e32 v0, 0xbfb8aa3b, v188
	v_exp_f32_e32 v0, v0
	v_pk_mul_f32 v[152:153], v[152:153], v[190:191]
	v_pk_add_f32 v[190:191], v[94:95], v[138:139]
	v_add_f32_e32 v0, 1.0, v0
	v_rcp_f32_e32 v188, v0
	v_mul_f32_e32 v0, 0xbfb8aa3b, v189
	v_exp_f32_e32 v0, v0
	s_nop 0
	v_add_f32_e32 v0, 1.0, v0
	v_rcp_f32_e32 v189, v0
	s_nop 0
	v_pk_mul_f32 v[150:151], v[150:151], v[188:189]
	v_lshlrev_b32_e32 v188, 16, v146
	v_and_b32_e32 v189, 0xffff0000, v146
	v_lshlrev_b32_e32 v146, 16, v147
	v_and_b32_e32 v147, 0xffff0000, v147
	v_pk_mul_f32 v[150:151], v[150:151], v[146:147]
	v_pk_mul_f32 v[146:147], v[152:153], v[188:189]
	v_pk_mul_f32 v[188:189], v[186:187], v[186:187]
	v_pk_mul_f32 v[152:153], v[164:165], v[164:165]
	v_pk_mul_f32 v[188:189], v[186:187], v[188:189]
	v_pk_mul_f32 v[152:153], v[164:165], v[152:153]
	v_pk_fma_f32 v[188:189], v[188:189], s[14:15], v[186:187] op_sel_hi:[1,0,1]
	v_pk_fma_f32 v[152:153], v[152:153], s[14:15], v[164:165] op_sel_hi:[1,0,1]
	v_pk_mul_f32 v[188:189], v[188:189], s[16:17] op_sel_hi:[1,0]
	v_pk_mul_f32 v[152:153], v[152:153], s[16:17] op_sel_hi:[1,0]
	v_mul_f32_e32 v0, 0xbfb8aa3b, v188
	v_exp_f32_e32 v0, v0
	v_cvt_pk_bf16_f32 v146, v146, v147
	v_cvt_pk_bf16_f32 v147, v150, v151
	v_pk_add_f32 v[150:151], v[104:105], v[144:145]
	v_add_f32_e32 v0, 1.0, v0
	v_rcp_f32_e32 v188, v0
	v_mul_f32_e32 v0, 0xbfb8aa3b, v189
	v_exp_f32_e32 v0, v0
	v_pk_mul_f32 v[192:193], v[150:151], v[150:151]
	v_add_f32_e32 v0, 1.0, v0
	v_rcp_f32_e32 v189, v0
	v_mul_f32_e32 v0, 0xbfb8aa3b, v152
	v_exp_f32_e32 v0, v0
	v_pk_mul_f32 v[192:193], v[150:151], v[192:193]
	v_add_f32_e32 v0, 1.0, v0
	v_rcp_f32_e32 v152, v0
	v_mul_f32_e32 v0, 0xbfb8aa3b, v153
	v_exp_f32_e32 v0, v0
	v_pk_fma_f32 v[192:193], v[192:193], s[14:15], v[150:151] op_sel_hi:[1,0,1]
	v_add_f32_e32 v0, 1.0, v0
	v_rcp_f32_e32 v153, v0
	v_or_b32_e32 v0, 48, v180
	v_pk_mul_f32 v[192:193], v[192:193], s[16:17] op_sel_hi:[1,0]
	v_pk_mul_f32 v[152:153], v[164:165], v[152:153]
	v_pk_mul_f32 v[164:165], v[186:187], v[188:189]
	v_lshlrev_b32_e32 v186, 16, v148
	v_and_b32_e32 v187, 0xffff0000, v148
	v_lshlrev_b32_e32 v148, 16, v149
	v_and_b32_e32 v149, 0xffff0000, v149
	v_pk_mul_f32 v[152:153], v[152:153], v[148:149]
	v_pk_mul_f32 v[148:149], v[164:165], v[186:187]
	v_mad_i64_i32 v[186:187], s[2:3], v0, s93, v[182:183]
	v_cvt_pk_bf16_f32 v148, v148, v149
	v_cvt_pk_bf16_f32 v149, v152, v153
	v_pk_add_f32 v[152:153], v[102:103], v[142:143]
	global_store_dwordx4 v[162:163], v[146:149], off offset:256
	v_pk_mul_f32 v[194:195], v[152:153], v[152:153]
	s_waitcnt vmcnt(6)
	v_add_u32_e32 v250, 0x90, v180
	v_mad_i64_i32 v[252:253], s[2:3], v250, s93, v[182:183]
	v_mov_b64_e32 v[162:163], v[204:205]
	v_mov_b64_e32 v[164:165], v[206:207]
	v_mov_b64_e32 v[146:147], v[242:243]
	v_mov_b64_e32 v[148:149], v[244:245]
	global_load_dwordx4 v[204:207], v[252:253], off
	global_load_dwordx4 v[242:245], v[252:253], off offset:256
	v_pk_mul_f32 v[194:195], v[152:153], v[194:195]
	s_nop 0
	v_pk_add_f32 v[188:189], v[96:97], v[140:141]
	v_pk_fma_f32 v[194:195], v[194:195], s[14:15], v[152:153] op_sel_hi:[1,0,1]
	s_nop 0
	v_pk_mul_f32 v[194:195], v[194:195], s[16:17] op_sel_hi:[1,0]
	s_nop 0
	v_mul_f32_e32 v0, 0xbfb8aa3b, v194
	v_exp_f32_e32 v0, v0
	s_nop 0
	v_add_f32_e32 v0, 1.0, v0
	v_rcp_f32_e32 v194, v0
	v_mul_f32_e32 v0, 0xbfb8aa3b, v195
	v_exp_f32_e32 v0, v0
	s_nop 0
	v_add_f32_e32 v0, 1.0, v0
	v_rcp_f32_e32 v195, v0
	v_mul_f32_e32 v0, 0xbfb8aa3b, v192
	v_exp_f32_e32 v0, v0
	v_pk_mul_f32 v[152:153], v[152:153], v[194:195]
	v_add_f32_e32 v0, 1.0, v0
	v_rcp_f32_e32 v192, v0
	v_mul_f32_e32 v0, 0xbfb8aa3b, v193
	v_exp_f32_e32 v0, v0
	s_nop 0
	v_add_f32_e32 v0, 1.0, v0
	v_rcp_f32_e32 v193, v0
	s_nop 0
	v_pk_mul_f32 v[150:151], v[150:151], v[192:193]
	v_lshlrev_b32_e32 v192, 16, v158
	v_and_b32_e32 v193, 0xffff0000, v158
	v_lshlrev_b32_e32 v158, 16, v159
	v_and_b32_e32 v159, 0xffff0000, v159
	v_pk_mul_f32 v[158:159], v[150:151], v[158:159]
	v_pk_mul_f32 v[150:151], v[152:153], v[192:193]
	v_pk_mul_f32 v[192:193], v[190:191], v[190:191]
	v_pk_mul_f32 v[152:153], v[188:189], v[188:189]
	v_pk_mul_f32 v[192:193], v[190:191], v[192:193]
	v_pk_mul_f32 v[152:153], v[188:189], v[152:153]
	v_pk_fma_f32 v[192:193], v[192:193], s[14:15], v[190:191] op_sel_hi:[1,0,1]
	v_pk_fma_f32 v[152:153], v[152:153], s[14:15], v[188:189] op_sel_hi:[1,0,1]
	v_pk_mul_f32 v[192:193], v[192:193], s[16:17] op_sel_hi:[1,0]
	v_pk_mul_f32 v[152:153], v[152:153], s[16:17] op_sel_hi:[1,0]
	v_mul_f32_e32 v0, 0xbfb8aa3b, v192
	v_exp_f32_e32 v0, v0
	v_cvt_pk_bf16_f32 v150, v150, v151
	v_cvt_pk_bf16_f32 v151, v158, v159
	v_pk_add_f32 v[158:159], v[76:77], v[132:133]
	v_add_f32_e32 v0, 1.0, v0
	v_rcp_f32_e32 v192, v0
	v_mul_f32_e32 v0, 0xbfb8aa3b, v193
	v_exp_f32_e32 v0, v0
	s_nop 0
	v_add_f32_e32 v0, 1.0, v0
	v_rcp_f32_e32 v193, v0
	v_mul_f32_e32 v0, 0xbfb8aa3b, v152
	v_exp_f32_e32 v0, v0
	s_nop 0
	v_add_f32_e32 v0, 1.0, v0
	v_rcp_f32_e32 v152, v0
	v_mul_f32_e32 v0, 0xbfb8aa3b, v153
	v_exp_f32_e32 v0, v0
	s_nop 0
	v_add_f32_e32 v0, 1.0, v0
	v_rcp_f32_e32 v153, v0
	s_nop 0
	v_pk_mul_f32 v[152:153], v[188:189], v[152:153]
; __device__ __forceinline__ f32x4 gelu4(const f32x4 x) { const f32x4 u = (x + x * x * x * 0.044715f) * 1.5957691216f; return x * sigmoid4(u); }
; __device__ __forceinline__ float bf_lo(unsigned w) { return __uint_as_float(w << 16); }
; __device__ __forceinline__ float bf_hi(unsigned w) { return __uint_as_float(w & 0xffff0000u); }
; __device__ __forceinline__ u32x4 pack8(const f32x4 a, const f32x4 b) { u32x4 w; w.x = cvt_pk_bf16(a[0], a[1]); w.y = cvt_pk_bf16(a[2], a[3]); w.z = cvt_pk_bf16(b[0], b[1]); w.w = cvt_pk_bf16(b[2], b[3]); return w; }
;     __device__ __forceinline__ void operator()(const f32x4 (&acc)[2][2][4][2], const pg8::Unit& u_in, int wr, int wc, int fr, int fq) const {
;     ...
;             for (int ai = 0; ai < 2; ++ai)
; #pragma unroll
;                 for (int m = 0; m < 4; ++m) { bf16_t* rowp = o0 + (size_t)(row0 + ai * 128 + m * 16) * ldc + col0;
;                     if (ai * 4 + m < 7) { const int nx = ai * 4 + m + 1; const bf16_t* np = o0 + (size_t)(row0 + (nx >> 2) * 128 + (nx & 3) * 16) * ldc + col0; qn[0] = *(const u32x4*)np; qn[1] = *(const u32x4*)(np + 128); }
;                     asm volatile("" : "+v"(qc[0]), "+v"(qc[1]));
; #pragma unroll
;                     for (int bj = 0; bj < 2; ++bj) { f32x4 v0 = acc[ai][bj][m][0] + bv[bj][0], v1 = acc[ai][bj][m][1] + bv[bj][1];
;                         const u32x4 q = qc[bj];
;                         v0 = gelu4(v0) * (f32x4){bf_lo(q.x), bf_hi(q.x), bf_lo(q.y), bf_hi(q.y)}; v1 = gelu4(v1) * (f32x4){bf_lo(q.z), bf_hi(q.z), bf_lo(q.w), bf_hi(q.w)};
;                         *(u32x4*)(rowp + bj * 128) = pack8(v0, v1); }
;                     qc[0] = qn[0]; qc[1] = qn[1]; }
	v_pk_mul_f32 v[188:189], v[190:191], v[192:193]
	v_lshlrev_b32_e32 v190, 16, v160
	v_and_b32_e32 v191, 0xffff0000, v160
	v_lshlrev_b32_e32 v160, 16, v161
	v_and_b32_e32 v161, 0xffff0000, v161
	v_pk_mul_f32 v[160:161], v[152:153], v[160:161]
	v_pk_mul_f32 v[152:153], v[188:189], v[190:191]
	s_nop 0
	v_cvt_pk_bf16_f32 v152, v152, v153
	v_cvt_pk_bf16_f32 v153, v160, v161
	global_store_dwordx4 v[184:185], v[150:153], off
	v_pk_add_f32 v[160:161], v[74:75], v[130:131]
	s_nop 0
	v_pk_add_f32 v[152:153], v[82:83], v[134:135]
	v_pk_add_f32 v[150:151], v[84:85], v[136:137]
	v_pk_mul_f32 v[190:191], v[152:153], v[152:153]
	v_pk_mul_f32 v[188:189], v[150:151], v[150:151]
	v_pk_mul_f32 v[190:191], v[152:153], v[190:191]
	v_pk_mul_f32 v[188:189], v[150:151], v[188:189]
	v_pk_fma_f32 v[190:191], v[190:191], s[14:15], v[152:153] op_sel_hi:[1,0,1]
	v_pk_fma_f32 v[188:189], v[188:189], s[14:15], v[150:151] op_sel_hi:[1,0,1]
	v_pk_mul_f32 v[190:191], v[190:191], s[16:17] op_sel_hi:[1,0]
	v_pk_mul_f32 v[188:189], v[188:189], s[16:17] op_sel_hi:[1,0]
	v_mul_f32_e32 v0, 0xbfb8aa3b, v190
	v_exp_f32_e32 v0, v0
	s_nop 0
	v_add_f32_e32 v0, 1.0, v0
	v_rcp_f32_e32 v190, v0
	v_mul_f32_e32 v0, 0xbfb8aa3b, v191
	v_exp_f32_e32 v0, v0
	s_nop 0
	v_add_f32_e32 v0, 1.0, v0
	v_rcp_f32_e32 v191, v0
	v_mul_f32_e32 v0, 0xbfb8aa3b, v188
	v_exp_f32_e32 v0, v0
	v_pk_mul_f32 v[152:153], v[152:153], v[190:191]
	v_pk_add_f32 v[190:191], v[78:79], v[138:139]
	v_add_f32_e32 v0, 1.0, v0
	v_rcp_f32_e32 v188, v0
	v_mul_f32_e32 v0, 0xbfb8aa3b, v189
	v_exp_f32_e32 v0, v0
	s_nop 0
	v_add_f32_e32 v0, 1.0, v0
	v_rcp_f32_e32 v189, v0
	s_nop 0
	v_pk_mul_f32 v[150:151], v[150:151], v[188:189]
	v_lshlrev_b32_e32 v188, 16, v154
	v_and_b32_e32 v189, 0xffff0000, v154
	v_lshlrev_b32_e32 v154, 16, v155
	v_and_b32_e32 v155, 0xffff0000, v155
	v_pk_mul_f32 v[154:155], v[150:151], v[154:155]
	v_pk_mul_f32 v[150:151], v[152:153], v[188:189]
	v_pk_mul_f32 v[188:189], v[160:161], v[160:161]
	v_pk_mul_f32 v[152:153], v[158:159], v[158:159]
	v_pk_mul_f32 v[188:189], v[160:161], v[188:189]
	v_pk_mul_f32 v[152:153], v[158:159], v[152:153]
	v_pk_fma_f32 v[188:189], v[188:189], s[14:15], v[160:161] op_sel_hi:[1,0,1]
	v_pk_fma_f32 v[152:153], v[152:153], s[14:15], v[158:159] op_sel_hi:[1,0,1]
	v_pk_mul_f32 v[188:189], v[188:189], s[16:17] op_sel_hi:[1,0]
	v_pk_mul_f32 v[152:153], v[152:153], s[16:17] op_sel_hi:[1,0]
	v_mul_f32_e32 v0, 0xbfb8aa3b, v188
	v_exp_f32_e32 v0, v0
	v_cvt_pk_bf16_f32 v150, v150, v151
	v_cvt_pk_bf16_f32 v151, v154, v155
	s_nop 0
	v_add_f32_e32 v0, 1.0, v0
	v_rcp_f32_e32 v188, v0
	v_mul_f32_e32 v0, 0xbfb8aa3b, v189
	v_exp_f32_e32 v0, v0
	s_nop 0
	v_add_f32_e32 v0, 1.0, v0
	v_rcp_f32_e32 v189, v0
	v_mul_f32_e32 v0, 0xbfb8aa3b, v152
	v_exp_f32_e32 v0, v0
	s_nop 0
	v_add_f32_e32 v0, 1.0, v0
	v_rcp_f32_e32 v152, v0
	v_mul_f32_e32 v0, 0xbfb8aa3b, v153
	v_exp_f32_e32 v0, v0
	s_nop 0
	v_add_f32_e32 v0, 1.0, v0
	v_rcp_f32_e32 v153, v0
	v_add_u32_e32 v0, 0x80, v180
	v_pk_mul_f32 v[152:153], v[158:159], v[152:153]
	v_pk_mul_f32 v[158:159], v[160:161], v[188:189]
	v_lshlrev_b32_e32 v160, 16, v156
	v_and_b32_e32 v161, 0xffff0000, v156
	v_lshlrev_b32_e32 v156, 16, v157
	v_and_b32_e32 v157, 0xffff0000, v157
	v_pk_mul_f32 v[156:157], v[152:153], v[156:157]
	v_pk_mul_f32 v[152:153], v[158:159], v[160:161]
	v_pk_add_f32 v[160:161], v[86:87], v[142:143]
	v_cvt_pk_bf16_f32 v152, v152, v153
	v_cvt_pk_bf16_f32 v153, v156, v157
	global_store_dwordx4 v[184:185], v[150:153], off offset:256
	v_pk_mul_f32 v[194:195], v[160:161], v[160:161]
	v_mad_i64_i32 v[184:185], s[2:3], v0, s93, v[182:183]
	v_pk_mul_f32 v[194:195], v[160:161], v[194:195]
	v_pk_add_f32 v[158:159], v[88:89], v[144:145]
	v_pk_fma_f32 v[194:195], v[194:195], s[14:15], v[160:161] op_sel_hi:[1,0,1]
	v_pk_mul_f32 v[192:193], v[158:159], v[158:159]
	v_pk_mul_f32 v[194:195], v[194:195], s[16:17] op_sel_hi:[1,0]
	v_pk_mul_f32 v[192:193], v[158:159], v[192:193]
	v_mul_f32_e32 v0, 0xbfb8aa3b, v194
	v_exp_f32_e32 v0, v0
	v_pk_fma_f32 v[192:193], v[192:193], s[14:15], v[158:159] op_sel_hi:[1,0,1]
	s_waitcnt vmcnt(6)
	v_add_u32_e32 v250, 0xa0, v180
	v_mad_i64_i32 v[252:253], s[2:3], v250, s93, v[182:183]
	v_mov_b64_e32 v[154:155], v[196:197]
	v_mov_b64_e32 v[156:157], v[198:199]
	v_mov_b64_e32 v[150:151], v[200:201]
	v_mov_b64_e32 v[152:153], v[202:203]
	global_load_dwordx4 v[196:199], v[252:253], off
	global_load_dwordx4 v[200:203], v[252:253], off offset:256
	v_pk_mul_f32 v[192:193], v[192:193], s[16:17] op_sel_hi:[1,0]
	v_add_f32_e32 v0, 1.0, v0
	v_rcp_f32_e32 v194, v0
	v_mul_f32_e32 v0, 0xbfb8aa3b, v195
	v_exp_f32_e32 v0, v0
	s_nop 0
	v_pk_add_f32 v[188:189], v[80:81], v[140:141]
	v_add_f32_e32 v0, 1.0, v0
	v_rcp_f32_e32 v195, v0
	v_mul_f32_e32 v0, 0xbfb8aa3b, v192
	v_exp_f32_e32 v0, v0
	v_pk_mul_f32 v[160:161], v[160:161], v[194:195]
	v_add_f32_e32 v0, 1.0, v0
	v_rcp_f32_e32 v192, v0
	v_mul_f32_e32 v0, 0xbfb8aa3b, v193
	v_exp_f32_e32 v0, v0
	s_nop 0
	v_add_f32_e32 v0, 1.0, v0
	v_rcp_f32_e32 v193, v0
	s_nop 0
	v_pk_mul_f32 v[158:159], v[158:159], v[192:193]
	v_lshlrev_b32_e32 v192, 16, v162
	v_and_b32_e32 v193, 0xffff0000, v162
	v_lshlrev_b32_e32 v162, 16, v163
	v_and_b32_e32 v163, 0xffff0000, v163
	v_pk_mul_f32 v[162:163], v[158:159], v[162:163]
	v_pk_mul_f32 v[158:159], v[160:161], v[192:193]
	v_pk_mul_f32 v[192:193], v[190:191], v[190:191]
	v_pk_mul_f32 v[160:161], v[188:189], v[188:189]
	v_pk_mul_f32 v[192:193], v[190:191], v[192:193]
	v_pk_mul_f32 v[160:161], v[188:189], v[160:161]
	v_pk_fma_f32 v[192:193], v[192:193], s[14:15], v[190:191] op_sel_hi:[1,0,1]
	v_pk_fma_f32 v[160:161], v[160:161], s[14:15], v[188:189] op_sel_hi:[1,0,1]
; __device__ __forceinline__ f32x4 gelu4(const f32x4 x) { const f32x4 u = (x + x * x * x * 0.044715f) * 1.5957691216f; return x * sigmoid4(u); }
; __device__ __forceinline__ float bf_lo(unsigned w) { return __uint_as_float(w << 16); }
; __device__ __forceinline__ float bf_hi(unsigned w) { return __uint_as_float(w & 0xffff0000u); }
; __device__ __forceinline__ u32x4 pack8(const f32x4 a, const f32x4 b) { u32x4 w; w.x = cvt_pk_bf16(a[0], a[1]); w.y = cvt_pk_bf16(a[2], a[3]); w.z = cvt_pk_bf16(b[0], b[1]); w.w = cvt_pk_bf16(b[2], b[3]); return w; }
;     __device__ __forceinline__ void operator()(const f32x4 (&acc)[2][2][4][2], const pg8::Unit& u_in, int wr, int wc, int fr, int fq) const {
;     ...
;             for (int ai = 0; ai < 2; ++ai)
; #pragma unroll
;                 for (int m = 0; m < 4; ++m) { bf16_t* rowp = o0 + (size_t)(row0 + ai * 128 + m * 16) * ldc + col0;
;                     if (ai * 4 + m < 7) { const int nx = ai * 4 + m + 1; const bf16_t* np = o0 + (size_t)(row0 + (nx >> 2) * 128 + (nx & 3) * 16) * ldc + col0; qn[0] = *(const u32x4*)np; qn[1] = *(const u32x4*)(np + 128); }
;                     asm volatile("" : "+v"(qc[0]), "+v"(qc[1]));
; #pragma unroll
;                     for (int bj = 0; bj < 2; ++bj) { f32x4 v0 = acc[ai][bj][m][0] + bv[bj][0], v1 = acc[ai][bj][m][1] + bv[bj][1];
;                         const u32x4 q = qc[bj];
;                         v0 = gelu4(v0) * (f32x4){bf_lo(q.x), bf_hi(q.x), bf_lo(q.y), bf_hi(q.y)}; v1 = gelu4(v1) * (f32x4){bf_lo(q.z), bf_hi(q.z), bf_lo(q.w), bf_hi(q.w)};
;                         *(u32x4*)(rowp + bj * 128) = pack8(v0, v1); }
;                     qc[0] = qn[0]; qc[1] = qn[1]; }
	v_pk_mul_f32 v[192:193], v[192:193], s[16:17] op_sel_hi:[1,0]
	v_pk_mul_f32 v[160:161], v[160:161], s[16:17] op_sel_hi:[1,0]
	v_mul_f32_e32 v0, 0xbfb8aa3b, v192
	v_exp_f32_e32 v0, v0
	v_cvt_pk_bf16_f32 v158, v158, v159
	v_cvt_pk_bf16_f32 v159, v162, v163
	v_pk_add_f32 v[162:163], v[68:69], v[132:133]
	v_add_f32_e32 v0, 1.0, v0
	v_rcp_f32_e32 v192, v0
	v_mul_f32_e32 v0, 0xbfb8aa3b, v193
	v_exp_f32_e32 v0, v0
	s_nop 0
	v_add_f32_e32 v0, 1.0, v0
	v_rcp_f32_e32 v193, v0
	v_mul_f32_e32 v0, 0xbfb8aa3b, v160
	v_exp_f32_e32 v0, v0
	s_nop 0
	v_add_f32_e32 v0, 1.0, v0
	v_rcp_f32_e32 v160, v0
	v_mul_f32_e32 v0, 0xbfb8aa3b, v161
	v_exp_f32_e32 v0, v0
	s_nop 0
	v_add_f32_e32 v0, 1.0, v0
	v_rcp_f32_e32 v161, v0
	s_nop 0
	v_pk_mul_f32 v[160:161], v[188:189], v[160:161]
	v_pk_mul_f32 v[188:189], v[190:191], v[192:193]
	v_lshlrev_b32_e32 v190, 16, v164
	v_and_b32_e32 v191, 0xffff0000, v164
	v_lshlrev_b32_e32 v164, 16, v165
	v_and_b32_e32 v165, 0xffff0000, v165
	v_pk_mul_f32 v[164:165], v[160:161], v[164:165]
	v_pk_mul_f32 v[160:161], v[188:189], v[190:191]
	s_nop 0
	v_cvt_pk_bf16_f32 v160, v160, v161
	v_cvt_pk_bf16_f32 v161, v164, v165
	global_store_dwordx4 v[186:187], v[158:161], off
	v_pk_add_f32 v[164:165], v[66:67], v[130:131]
	s_nop 0
	v_pk_add_f32 v[160:161], v[70:71], v[134:135]
	v_pk_add_f32 v[158:159], v[72:73], v[136:137]
	v_pk_mul_f32 v[190:191], v[160:161], v[160:161]
	v_pk_mul_f32 v[188:189], v[158:159], v[158:159]
	v_pk_mul_f32 v[190:191], v[160:161], v[190:191]
	v_pk_mul_f32 v[188:189], v[158:159], v[188:189]
	v_pk_fma_f32 v[190:191], v[190:191], s[14:15], v[160:161] op_sel_hi:[1,0,1]
	v_pk_fma_f32 v[188:189], v[188:189], s[14:15], v[158:159] op_sel_hi:[1,0,1]
	v_pk_mul_f32 v[190:191], v[190:191], s[16:17] op_sel_hi:[1,0]
	v_pk_mul_f32 v[188:189], v[188:189], s[16:17] op_sel_hi:[1,0]
	v_mul_f32_e32 v0, 0xbfb8aa3b, v190
	v_exp_f32_e32 v0, v0
	s_nop 0
	v_add_f32_e32 v0, 1.0, v0
	v_rcp_f32_e32 v190, v0
	v_mul_f32_e32 v0, 0xbfb8aa3b, v191
	v_exp_f32_e32 v0, v0
	s_nop 0
	v_add_f32_e32 v0, 1.0, v0
	v_rcp_f32_e32 v191, v0
	v_mul_f32_e32 v0, 0xbfb8aa3b, v188
	v_exp_f32_e32 v0, v0
	v_pk_mul_f32 v[160:161], v[160:161], v[190:191]
	v_pk_add_f32 v[190:191], v[58:59], v[138:139]
	v_add_f32_e32 v0, 1.0, v0
	v_rcp_f32_e32 v188, v0
	v_mul_f32_e32 v0, 0xbfb8aa3b, v189
	v_exp_f32_e32 v0, v0
	s_nop 0
	v_add_f32_e32 v0, 1.0, v0
	v_rcp_f32_e32 v189, v0
	s_nop 0
	v_pk_mul_f32 v[158:159], v[158:159], v[188:189]
	v_lshlrev_b32_e32 v188, 16, v146
	v_and_b32_e32 v189, 0xffff0000, v146
	v_lshlrev_b32_e32 v146, 16, v147
	v_and_b32_e32 v147, 0xffff0000, v147
	v_pk_mul_f32 v[158:159], v[158:159], v[146:147]
	v_pk_mul_f32 v[146:147], v[160:161], v[188:189]
	v_pk_mul_f32 v[188:189], v[164:165], v[164:165]
	v_pk_mul_f32 v[160:161], v[162:163], v[162:163]
	v_pk_mul_f32 v[188:189], v[164:165], v[188:189]
	v_pk_mul_f32 v[160:161], v[162:163], v[160:161]
	v_pk_fma_f32 v[188:189], v[188:189], s[14:15], v[164:165] op_sel_hi:[1,0,1]
	v_pk_fma_f32 v[160:161], v[160:161], s[14:15], v[162:163] op_sel_hi:[1,0,1]
	v_pk_mul_f32 v[188:189], v[188:189], s[16:17] op_sel_hi:[1,0]
	v_pk_mul_f32 v[160:161], v[160:161], s[16:17] op_sel_hi:[1,0]
	v_mul_f32_e32 v0, 0xbfb8aa3b, v188
	v_exp_f32_e32 v0, v0
	v_cvt_pk_bf16_f32 v146, v146, v147
	v_cvt_pk_bf16_f32 v147, v158, v159
	s_nop 0
	v_add_f32_e32 v0, 1.0, v0
	v_rcp_f32_e32 v188, v0
	v_mul_f32_e32 v0, 0xbfb8aa3b, v189
	v_exp_f32_e32 v0, v0
	s_nop 0
	v_add_f32_e32 v0, 1.0, v0
	v_rcp_f32_e32 v189, v0
	v_mul_f32_e32 v0, 0xbfb8aa3b, v160
	v_exp_f32_e32 v0, v0
	s_nop 0
	v_add_f32_e32 v0, 1.0, v0
	v_rcp_f32_e32 v160, v0
	v_mul_f32_e32 v0, 0xbfb8aa3b, v161
	v_exp_f32_e32 v0, v0
	s_nop 0
	v_add_f32_e32 v0, 1.0, v0
	v_rcp_f32_e32 v161, v0
	v_add_u32_e32 v0, 0x90, v180
	v_pk_mul_f32 v[160:161], v[162:163], v[160:161]
	v_pk_mul_f32 v[162:163], v[164:165], v[188:189]
	v_lshlrev_b32_e32 v164, 16, v148
	v_and_b32_e32 v165, 0xffff0000, v148
	v_lshlrev_b32_e32 v148, 16, v149
	v_and_b32_e32 v149, 0xffff0000, v149
	v_pk_mul_f32 v[160:161], v[160:161], v[148:149]
	v_pk_mul_f32 v[148:149], v[162:163], v[164:165]
	v_mad_i64_i32 v[162:163], s[2:3], v0, s93, v[182:183]
	v_cvt_pk_bf16_f32 v148, v148, v149
	v_cvt_pk_bf16_f32 v149, v160, v161
	global_store_dwordx4 v[186:187], v[146:149], off offset:256
	v_pk_add_f32 v[186:187], v[62:63], v[142:143]
	v_pk_add_f32 v[164:165], v[64:65], v[144:145]
	v_pk_mul_f32 v[194:195], v[186:187], v[186:187]
	v_pk_mul_f32 v[192:193], v[164:165], v[164:165]
	v_pk_mul_f32 v[194:195], v[186:187], v[194:195]
	v_pk_mul_f32 v[192:193], v[164:165], v[192:193]
	v_pk_fma_f32 v[194:195], v[194:195], s[14:15], v[186:187] op_sel_hi:[1,0,1]
	v_pk_fma_f32 v[192:193], v[192:193], s[14:15], v[164:165] op_sel_hi:[1,0,1]
	v_pk_mul_f32 v[194:195], v[194:195], s[16:17] op_sel_hi:[1,0]
	v_pk_mul_f32 v[192:193], v[192:193], s[16:17] op_sel_hi:[1,0]
	v_mul_f32_e32 v0, 0xbfb8aa3b, v194
	v_exp_f32_e32 v0, v0
	s_waitcnt vmcnt(6)
; __device__ __forceinline__ f32x4 gelu4(const f32x4 x) { const f32x4 u = (x + x * x * x * 0.044715f) * 1.5957691216f; return x * sigmoid4(u); }
; __device__ __forceinline__ float bf_lo(unsigned w) { return __uint_as_float(w << 16); }
; __device__ __forceinline__ float bf_hi(unsigned w) { return __uint_as_float(w & 0xffff0000u); }
; __device__ __forceinline__ u32x4 pack8(const f32x4 a, const f32x4 b) { u32x4 w; w.x = cvt_pk_bf16(a[0], a[1]); w.y = cvt_pk_bf16(a[2], a[3]); w.z = cvt_pk_bf16(b[0], b[1]); w.w = cvt_pk_bf16(b[2], b[3]); return w; }
;     __device__ __forceinline__ void operator()(const f32x4 (&acc)[2][2][4][2], const pg8::Unit& u_in, int wr, int wc, int fr, int fq) const {
;     ...
;             for (int ai = 0; ai < 2; ++ai)
; #pragma unroll
;                 for (int m = 0; m < 4; ++m) { bf16_t* rowp = o0 + (size_t)(row0 + ai * 128 + m * 16) * ldc + col0;
;                     if (ai * 4 + m < 7) { const int nx = ai * 4 + m + 1; const bf16_t* np = o0 + (size_t)(row0 + (nx >> 2) * 128 + (nx & 3) * 16) * ldc + col0; qn[0] = *(const u32x4*)np; qn[1] = *(const u32x4*)(np + 128); }
;                     asm volatile("" : "+v"(qc[0]), "+v"(qc[1]));
; #pragma unroll
;                     for (int bj = 0; bj < 2; ++bj) { f32x4 v0 = acc[ai][bj][m][0] + bv[bj][0], v1 = acc[ai][bj][m][1] + bv[bj][1];
;                         const u32x4 q = qc[bj];
;                         v0 = gelu4(v0) * (f32x4){bf_lo(q.x), bf_hi(q.x), bf_lo(q.y), bf_hi(q.y)}; v1 = gelu4(v1) * (f32x4){bf_lo(q.z), bf_hi(q.z), bf_lo(q.w), bf_hi(q.w)};
;                         *(u32x4*)(rowp + bj * 128) = pack8(v0, v1); }
;                     qc[0] = qn[0]; qc[1] = qn[1]; }
	v_add_u32_e32 v250, 0xb0, v180
	v_mad_i64_i32 v[252:253], s[2:3], v250, s93, v[182:183]
	v_mov_b64_e32 v[158:159], v[204:205]
	v_mov_b64_e32 v[160:161], v[206:207]
	v_mov_b64_e32 v[146:147], v[242:243]
	v_mov_b64_e32 v[148:149], v[244:245]
	global_load_dwordx4 v[204:207], v[252:253], off
	global_load_dwordx4 v[242:245], v[252:253], off offset:256
	s_nop 0
	v_pk_add_f32 v[188:189], v[60:61], v[140:141]
	v_add_f32_e32 v0, 1.0, v0
	v_rcp_f32_e32 v194, v0
	v_mul_f32_e32 v0, 0xbfb8aa3b, v195
	v_exp_f32_e32 v0, v0
	s_nop 0
	v_add_f32_e32 v0, 1.0, v0
	v_rcp_f32_e32 v195, v0
	v_mul_f32_e32 v0, 0xbfb8aa3b, v192
	v_exp_f32_e32 v0, v0
	v_pk_mul_f32 v[186:187], v[186:187], v[194:195]
	v_add_f32_e32 v0, 1.0, v0
	v_rcp_f32_e32 v192, v0
	v_mul_f32_e32 v0, 0xbfb8aa3b, v193
	v_exp_f32_e32 v0, v0
	s_nop 0
	v_add_f32_e32 v0, 1.0, v0
	v_rcp_f32_e32 v193, v0
	s_nop 0
	v_pk_mul_f32 v[164:165], v[164:165], v[192:193]
	v_lshlrev_b32_e32 v192, 16, v154
	v_and_b32_e32 v193, 0xffff0000, v154
	v_lshlrev_b32_e32 v154, 16, v155
	v_and_b32_e32 v155, 0xffff0000, v155
	v_pk_mul_f32 v[164:165], v[164:165], v[154:155]
	v_pk_mul_f32 v[154:155], v[186:187], v[192:193]
	v_pk_mul_f32 v[192:193], v[190:191], v[190:191]
	v_pk_mul_f32 v[186:187], v[188:189], v[188:189]
	v_pk_mul_f32 v[192:193], v[190:191], v[192:193]
	v_pk_mul_f32 v[186:187], v[188:189], v[186:187]
	v_pk_fma_f32 v[192:193], v[192:193], s[14:15], v[190:191] op_sel_hi:[1,0,1]
	v_pk_fma_f32 v[186:187], v[186:187], s[14:15], v[188:189] op_sel_hi:[1,0,1]
	v_pk_mul_f32 v[192:193], v[192:193], s[16:17] op_sel_hi:[1,0]
	v_pk_mul_f32 v[186:187], v[186:187], s[16:17] op_sel_hi:[1,0]
	v_mul_f32_e32 v0, 0xbfb8aa3b, v192
	v_exp_f32_e32 v0, v0
	v_cvt_pk_bf16_f32 v154, v154, v155
	v_cvt_pk_bf16_f32 v155, v164, v165
	v_pk_add_f32 v[164:165], v[44:45], v[132:133]
	v_add_f32_e32 v0, 1.0, v0
	v_rcp_f32_e32 v192, v0
	v_mul_f32_e32 v0, 0xbfb8aa3b, v193
	v_exp_f32_e32 v0, v0
	s_nop 0
	v_add_f32_e32 v0, 1.0, v0
	v_rcp_f32_e32 v193, v0
	v_mul_f32_e32 v0, 0xbfb8aa3b, v186
	v_exp_f32_e32 v0, v0
	s_nop 0
	v_add_f32_e32 v0, 1.0, v0
	v_rcp_f32_e32 v186, v0
	v_mul_f32_e32 v0, 0xbfb8aa3b, v187
	v_exp_f32_e32 v0, v0
	s_nop 0
	v_add_f32_e32 v0, 1.0, v0
	v_rcp_f32_e32 v187, v0
	s_nop 0
	v_pk_mul_f32 v[186:187], v[188:189], v[186:187]
	v_pk_mul_f32 v[188:189], v[190:191], v[192:193]
	v_lshlrev_b32_e32 v190, 16, v156
	v_and_b32_e32 v191, 0xffff0000, v156
	v_lshlrev_b32_e32 v156, 16, v157
	v_and_b32_e32 v157, 0xffff0000, v157
	v_pk_mul_f32 v[186:187], v[186:187], v[156:157]
	v_pk_mul_f32 v[156:157], v[188:189], v[190:191]
	s_nop 0
	v_cvt_pk_bf16_f32 v156, v156, v157
	v_cvt_pk_bf16_f32 v157, v186, v187
	global_store_dwordx4 v[184:185], v[154:157], off
	v_pk_add_f32 v[186:187], v[42:43], v[130:131]
	s_nop 0
	v_pk_add_f32 v[156:157], v[50:51], v[134:135]
	v_pk_add_f32 v[154:155], v[52:53], v[136:137]
	v_pk_mul_f32 v[190:191], v[156:157], v[156:157]
	v_pk_mul_f32 v[188:189], v[154:155], v[154:155]
	v_pk_mul_f32 v[190:191], v[156:157], v[190:191]
	v_pk_mul_f32 v[188:189], v[154:155], v[188:189]
	v_pk_fma_f32 v[190:191], v[190:191], s[14:15], v[156:157] op_sel_hi:[1,0,1]
	v_pk_fma_f32 v[188:189], v[188:189], s[14:15], v[154:155] op_sel_hi:[1,0,1]
	v_pk_mul_f32 v[190:191], v[190:191], s[16:17] op_sel_hi:[1,0]
	v_pk_mul_f32 v[188:189], v[188:189], s[16:17] op_sel_hi:[1,0]
	v_mul_f32_e32 v0, 0xbfb8aa3b, v190
	v_exp_f32_e32 v0, v0
	s_nop 0
	v_add_f32_e32 v0, 1.0, v0
	v_rcp_f32_e32 v190, v0
	v_mul_f32_e32 v0, 0xbfb8aa3b, v191
	v_exp_f32_e32 v0, v0
	s_nop 0
	v_add_f32_e32 v0, 1.0, v0
	v_rcp_f32_e32 v191, v0
	v_mul_f32_e32 v0, 0xbfb8aa3b, v188
	v_exp_f32_e32 v0, v0
	v_pk_mul_f32 v[156:157], v[156:157], v[190:191]
	v_pk_add_f32 v[190:191], v[46:47], v[138:139]
	v_add_f32_e32 v0, 1.0, v0
	v_rcp_f32_e32 v188, v0
	v_mul_f32_e32 v0, 0xbfb8aa3b, v189
	v_exp_f32_e32 v0, v0
	s_nop 0
	v_add_f32_e32 v0, 1.0, v0
	v_rcp_f32_e32 v189, v0
	s_nop 0
	v_pk_mul_f32 v[154:155], v[154:155], v[188:189]
	v_lshlrev_b32_e32 v188, 16, v150
	v_and_b32_e32 v189, 0xffff0000, v150
	v_lshlrev_b32_e32 v150, 16, v151
	v_and_b32_e32 v151, 0xffff0000, v151
	v_pk_mul_f32 v[154:155], v[154:155], v[150:151]
	v_pk_mul_f32 v[150:151], v[156:157], v[188:189]
	v_pk_mul_f32 v[188:189], v[186:187], v[186:187]
	v_pk_mul_f32 v[156:157], v[164:165], v[164:165]
	v_pk_mul_f32 v[188:189], v[186:187], v[188:189]
	v_pk_mul_f32 v[156:157], v[164:165], v[156:157]
	v_pk_fma_f32 v[188:189], v[188:189], s[14:15], v[186:187] op_sel_hi:[1,0,1]
	v_pk_fma_f32 v[156:157], v[156:157], s[14:15], v[164:165] op_sel_hi:[1,0,1]
	v_pk_mul_f32 v[188:189], v[188:189], s[16:17] op_sel_hi:[1,0]
	v_pk_mul_f32 v[156:157], v[156:157], s[16:17] op_sel_hi:[1,0]
	v_mul_f32_e32 v0, 0xbfb8aa3b, v188
	v_exp_f32_e32 v0, v0
	v_cvt_pk_bf16_f32 v150, v150, v151
	v_cvt_pk_bf16_f32 v151, v154, v155
	s_nop 0
	v_add_f32_e32 v0, 1.0, v0
	v_rcp_f32_e32 v188, v0
	v_mul_f32_e32 v0, 0xbfb8aa3b, v189
	v_exp_f32_e32 v0, v0
	s_nop 0
	v_add_f32_e32 v0, 1.0, v0
	v_rcp_f32_e32 v189, v0
	v_mul_f32_e32 v0, 0xbfb8aa3b, v156
	v_exp_f32_e32 v0, v0
	s_nop 0
	v_add_f32_e32 v0, 1.0, v0
	v_rcp_f32_e32 v156, v0
	v_mul_f32_e32 v0, 0xbfb8aa3b, v157
	v_exp_f32_e32 v0, v0
	s_nop 0
	v_add_f32_e32 v0, 1.0, v0
	v_rcp_f32_e32 v157, v0
	v_add_u32_e32 v0, 0xa0, v180
	v_pk_mul_f32 v[156:157], v[164:165], v[156:157]
	v_pk_mul_f32 v[164:165], v[186:187], v[188:189]
	v_lshlrev_b32_e32 v186, 16, v152
	v_and_b32_e32 v187, 0xffff0000, v152
	v_lshlrev_b32_e32 v152, 16, v153
	v_and_b32_e32 v153, 0xffff0000, v153
	v_pk_mul_f32 v[156:157], v[156:157], v[152:153]
	v_pk_mul_f32 v[152:153], v[164:165], v[186:187]
	v_pk_add_f32 v[186:187], v[54:55], v[142:143]
	v_mad_i64_i32 v[164:165], s[2:3], v0, s93, v[182:183]
	v_pk_mul_f32 v[194:195], v[186:187], v[186:187]
	v_cvt_pk_bf16_f32 v152, v152, v153
	v_cvt_pk_bf16_f32 v153, v156, v157
	global_store_dwordx4 v[184:185], v[150:153], off offset:256
	v_pk_mul_f32 v[194:195], v[186:187], v[194:195]
	v_pk_add_f32 v[184:185], v[56:57], v[144:145]
	v_pk_fma_f32 v[194:195], v[194:195], s[14:15], v[186:187] op_sel_hi:[1,0,1]
	v_pk_mul_f32 v[192:193], v[184:185], v[184:185]
	v_pk_mul_f32 v[194:195], v[194:195], s[16:17] op_sel_hi:[1,0]
	v_pk_mul_f32 v[192:193], v[184:185], v[192:193]
	v_mul_f32_e32 v0, 0xbfb8aa3b, v194
	v_exp_f32_e32 v0, v0
	v_pk_fma_f32 v[192:193], v[192:193], s[14:15], v[184:185] op_sel_hi:[1,0,1]
	s_waitcnt vmcnt(6)
; __device__ __forceinline__ f32x4 gelu4(const f32x4 x) { const f32x4 u = (x + x * x * x * 0.044715f) * 1.5957691216f; return x * sigmoid4(u); }
; __device__ __forceinline__ float bf_lo(unsigned w) { return __uint_as_float(w << 16); }
; __device__ __forceinline__ float bf_hi(unsigned w) { return __uint_as_float(w & 0xffff0000u); }
; __device__ __forceinline__ u32x4 pack8(const f32x4 a, const f32x4 b) { u32x4 w; w.x = cvt_pk_bf16(a[0], a[1]); w.y = cvt_pk_bf16(a[2], a[3]); w.z = cvt_pk_bf16(b[0], b[1]); w.w = cvt_pk_bf16(b[2], b[3]); return w; }
;     __device__ __forceinline__ void operator()(const f32x4 (&acc)[2][2][4][2], const pg8::Unit& u_in, int wr, int wc, int fr, int fq) const {
;     ...
;             for (int ai = 0; ai < 2; ++ai)
; #pragma unroll
;                 for (int m = 0; m < 4; ++m) { bf16_t* rowp = o0 + (size_t)(row0 + ai * 128 + m * 16) * ldc + col0;
;                     if (ai * 4 + m < 7) { const int nx = ai * 4 + m + 1; const bf16_t* np = o0 + (size_t)(row0 + (nx >> 2) * 128 + (nx & 3) * 16) * ldc + col0; qn[0] = *(const u32x4*)np; qn[1] = *(const u32x4*)(np + 128); }
;                     asm volatile("" : "+v"(qc[0]), "+v"(qc[1]));
; #pragma unroll
;                     for (int bj = 0; bj < 2; ++bj) { f32x4 v0 = acc[ai][bj][m][0] + bv[bj][0], v1 = acc[ai][bj][m][1] + bv[bj][1];
;                         const u32x4 q = qc[bj];
;                         v0 = gelu4(v0) * (f32x4){bf_lo(q.x), bf_hi(q.x), bf_lo(q.y), bf_hi(q.y)}; v1 = gelu4(v1) * (f32x4){bf_lo(q.z), bf_hi(q.z), bf_lo(q.w), bf_hi(q.w)};
;                         *(u32x4*)(rowp + bj * 128) = pack8(v0, v1); }
;                     qc[0] = qn[0]; qc[1] = qn[1]; }
	v_mov_b64_e32 v[154:155], v[196:197]
	v_mov_b64_e32 v[156:157], v[198:199]
	v_mov_b64_e32 v[150:151], v[200:201]
	v_mov_b64_e32 v[152:153], v[202:203]
	v_pk_mul_f32 v[192:193], v[192:193], s[16:17] op_sel_hi:[1,0]
	v_add_f32_e32 v0, 1.0, v0
	v_rcp_f32_e32 v194, v0
	v_mul_f32_e32 v0, 0xbfb8aa3b, v195
	v_exp_f32_e32 v0, v0
	s_nop 0
	v_pk_add_f32 v[188:189], v[48:49], v[140:141]
	v_add_f32_e32 v0, 1.0, v0
	v_rcp_f32_e32 v195, v0
	v_mul_f32_e32 v0, 0xbfb8aa3b, v192
	v_exp_f32_e32 v0, v0
	v_pk_mul_f32 v[186:187], v[186:187], v[194:195]
	v_add_f32_e32 v0, 1.0, v0
	v_rcp_f32_e32 v192, v0
	v_mul_f32_e32 v0, 0xbfb8aa3b, v193
	v_exp_f32_e32 v0, v0
	s_nop 0
	v_add_f32_e32 v0, 1.0, v0
	v_rcp_f32_e32 v193, v0
	s_nop 0
	v_pk_mul_f32 v[184:185], v[184:185], v[192:193]
	v_lshlrev_b32_e32 v192, 16, v158
	v_and_b32_e32 v193, 0xffff0000, v158
	v_lshlrev_b32_e32 v158, 16, v159
	v_and_b32_e32 v159, 0xffff0000, v159
	v_pk_mul_f32 v[184:185], v[184:185], v[158:159]
	v_pk_mul_f32 v[158:159], v[186:187], v[192:193]
	v_pk_mul_f32 v[192:193], v[190:191], v[190:191]
	v_pk_mul_f32 v[186:187], v[188:189], v[188:189]
	v_pk_mul_f32 v[192:193], v[190:191], v[192:193]
	v_pk_mul_f32 v[186:187], v[188:189], v[186:187]
	v_pk_fma_f32 v[192:193], v[192:193], s[14:15], v[190:191] op_sel_hi:[1,0,1]
	v_pk_fma_f32 v[186:187], v[186:187], s[14:15], v[188:189] op_sel_hi:[1,0,1]
	v_pk_mul_f32 v[192:193], v[192:193], s[16:17] op_sel_hi:[1,0]
	v_pk_mul_f32 v[186:187], v[186:187], s[16:17] op_sel_hi:[1,0]
	v_mul_f32_e32 v0, 0xbfb8aa3b, v192
	v_exp_f32_e32 v0, v0
	v_cvt_pk_bf16_f32 v158, v158, v159
	v_cvt_pk_bf16_f32 v159, v184, v185
	v_pk_add_f32 v[184:185], v[28:29], v[132:133]
	v_add_f32_e32 v0, 1.0, v0
	v_rcp_f32_e32 v192, v0
	v_mul_f32_e32 v0, 0xbfb8aa3b, v193
	v_exp_f32_e32 v0, v0
	s_nop 0
	v_add_f32_e32 v0, 1.0, v0
	v_rcp_f32_e32 v193, v0
	v_mul_f32_e32 v0, 0xbfb8aa3b, v186
	v_exp_f32_e32 v0, v0
	s_nop 0
	v_add_f32_e32 v0, 1.0, v0
	v_rcp_f32_e32 v186, v0
	v_mul_f32_e32 v0, 0xbfb8aa3b, v187
	v_exp_f32_e32 v0, v0
	s_nop 0
	v_add_f32_e32 v0, 1.0, v0
	v_rcp_f32_e32 v187, v0
	s_nop 0
	v_pk_mul_f32 v[186:187], v[188:189], v[186:187]
	v_pk_mul_f32 v[188:189], v[190:191], v[192:193]
	v_lshlrev_b32_e32 v190, 16, v160
	v_and_b32_e32 v191, 0xffff0000, v160
	v_lshlrev_b32_e32 v160, 16, v161
	v_and_b32_e32 v161, 0xffff0000, v161
	v_pk_mul_f32 v[186:187], v[186:187], v[160:161]
	v_pk_mul_f32 v[160:161], v[188:189], v[190:191]
	s_nop 0
	v_cvt_pk_bf16_f32 v160, v160, v161
	v_cvt_pk_bf16_f32 v161, v186, v187
	global_store_dwordx4 v[162:163], v[158:161], off
	v_pk_add_f32 v[186:187], v[26:27], v[130:131]
	s_nop 0
	v_pk_add_f32 v[160:161], v[34:35], v[134:135]
	v_pk_add_f32 v[158:159], v[36:37], v[136:137]
	v_pk_mul_f32 v[190:191], v[160:161], v[160:161]
	v_pk_mul_f32 v[188:189], v[158:159], v[158:159]
	v_pk_mul_f32 v[190:191], v[160:161], v[190:191]
	v_pk_mul_f32 v[188:189], v[158:159], v[188:189]
	v_pk_fma_f32 v[190:191], v[190:191], s[14:15], v[160:161] op_sel_hi:[1,0,1]
	v_pk_fma_f32 v[188:189], v[188:189], s[14:15], v[158:159] op_sel_hi:[1,0,1]
	v_pk_mul_f32 v[190:191], v[190:191], s[16:17] op_sel_hi:[1,0]
	v_pk_mul_f32 v[188:189], v[188:189], s[16:17] op_sel_hi:[1,0]
	v_mul_f32_e32 v0, 0xbfb8aa3b, v190
	v_exp_f32_e32 v0, v0
	s_nop 0
	v_add_f32_e32 v0, 1.0, v0
	v_rcp_f32_e32 v190, v0
	v_mul_f32_e32 v0, 0xbfb8aa3b, v191
	v_exp_f32_e32 v0, v0
	s_nop 0
	v_add_f32_e32 v0, 1.0, v0
	v_rcp_f32_e32 v191, v0
	v_mul_f32_e32 v0, 0xbfb8aa3b, v188
	v_exp_f32_e32 v0, v0
	v_pk_mul_f32 v[160:161], v[160:161], v[190:191]
	v_add_f32_e32 v0, 1.0, v0
	v_rcp_f32_e32 v188, v0
	v_mul_f32_e32 v0, 0xbfb8aa3b, v189
	v_exp_f32_e32 v0, v0
	s_nop 0
	v_add_f32_e32 v0, 1.0, v0
	v_rcp_f32_e32 v189, v0
	s_nop 0
	v_pk_mul_f32 v[158:159], v[158:159], v[188:189]
	v_lshlrev_b32_e32 v188, 16, v146
	v_and_b32_e32 v189, 0xffff0000, v146
	v_lshlrev_b32_e32 v146, 16, v147
	v_and_b32_e32 v147, 0xffff0000, v147
	v_pk_mul_f32 v[158:159], v[158:159], v[146:147]
	v_pk_mul_f32 v[146:147], v[160:161], v[188:189]
	v_pk_mul_f32 v[188:189], v[186:187], v[186:187]
	v_pk_mul_f32 v[160:161], v[184:185], v[184:185]
	v_pk_mul_f32 v[188:189], v[186:187], v[188:189]
	v_pk_mul_f32 v[160:161], v[184:185], v[160:161]
	v_pk_fma_f32 v[188:189], v[188:189], s[14:15], v[186:187] op_sel_hi:[1,0,1]
	v_pk_fma_f32 v[160:161], v[160:161], s[14:15], v[184:185] op_sel_hi:[1,0,1]
	v_pk_mul_f32 v[188:189], v[188:189], s[16:17] op_sel_hi:[1,0]
	v_pk_mul_f32 v[160:161], v[160:161], s[16:17] op_sel_hi:[1,0]
	v_mul_f32_e32 v0, 0xbfb8aa3b, v188
	v_exp_f32_e32 v0, v0
	v_cvt_pk_bf16_f32 v146, v146, v147
	v_cvt_pk_bf16_f32 v147, v158, v159
	s_nop 0
	v_add_f32_e32 v0, 1.0, v0
	v_rcp_f32_e32 v188, v0
	v_mul_f32_e32 v0, 0xbfb8aa3b, v189
	v_exp_f32_e32 v0, v0
	s_nop 0
	v_add_f32_e32 v0, 1.0, v0
	v_rcp_f32_e32 v189, v0
	v_mul_f32_e32 v0, 0xbfb8aa3b, v160
	v_exp_f32_e32 v0, v0
	s_nop 0
	v_add_f32_e32 v0, 1.0, v0
	v_rcp_f32_e32 v160, v0
	v_mul_f32_e32 v0, 0xbfb8aa3b, v161
	v_exp_f32_e32 v0, v0
	s_nop 0
	v_add_f32_e32 v0, 1.0, v0
	v_rcp_f32_e32 v161, v0
	v_add_u32_e32 v0, 0xb0, v180
	v_pk_mul_f32 v[160:161], v[184:185], v[160:161]
	v_pk_mul_f32 v[184:185], v[186:187], v[188:189]
	v_lshlrev_b32_e32 v186, 16, v148
	v_and_b32_e32 v187, 0xffff0000, v148
	v_lshlrev_b32_e32 v148, 16, v149
	v_and_b32_e32 v149, 0xffff0000, v149
	v_pk_mul_f32 v[160:161], v[160:161], v[148:149]
	v_pk_mul_f32 v[148:149], v[184:185], v[186:187]
	v_pk_add_f32 v[184:185], v[38:39], v[142:143]
	v_cvt_pk_bf16_f32 v148, v148, v149
	v_cvt_pk_bf16_f32 v149, v160, v161
	global_store_dwordx4 v[162:163], v[146:149], off offset:256
	v_pk_mul_f32 v[192:193], v[184:185], v[184:185]
	v_mad_i64_i32 v[162:163], s[2:3], v0, s93, v[182:183]
	v_pk_mul_f32 v[192:193], v[184:185], v[192:193]
	v_pk_add_f32 v[182:183], v[40:41], v[144:145]
	v_pk_fma_f32 v[192:193], v[192:193], s[14:15], v[184:185] op_sel_hi:[1,0,1]
	v_pk_mul_f32 v[190:191], v[182:183], v[182:183]
	v_pk_mul_f32 v[192:193], v[192:193], s[16:17] op_sel_hi:[1,0]
	v_pk_mul_f32 v[190:191], v[182:183], v[190:191]
	v_mul_f32_e32 v0, 0xbfb8aa3b, v192
	v_exp_f32_e32 v0, v0
	v_pk_fma_f32 v[190:191], v[190:191], s[14:15], v[182:183] op_sel_hi:[1,0,1]
	s_waitcnt vmcnt(4)
; __device__ __forceinline__ f32x4 gelu4(const f32x4 x) { const f32x4 u = (x + x * x * x * 0.044715f) * 1.5957691216f; return x * sigmoid4(u); }
; __device__ __forceinline__ float bf_lo(unsigned w) { return __uint_as_float(w << 16); }
; __device__ __forceinline__ float bf_hi(unsigned w) { return __uint_as_float(w & 0xffff0000u); }
; __device__ __forceinline__ u32x4 pack8(const f32x4 a, const f32x4 b) { u32x4 w; w.x = cvt_pk_bf16(a[0], a[1]); w.y = cvt_pk_bf16(a[2], a[3]); w.z = cvt_pk_bf16(b[0], b[1]); w.w = cvt_pk_bf16(b[2], b[3]); return w; }
;     __device__ __forceinline__ void operator()(const f32x4 (&acc)[2][2][4][2], const pg8::Unit& u_in, int wr, int wc, int fr, int fq) const {
;     ...
;             for (int ai = 0; ai < 2; ++ai)
; #pragma unroll
;                 for (int m = 0; m < 4; ++m) { bf16_t* rowp = o0 + (size_t)(row0 + ai * 128 + m * 16) * ldc + col0;
;                     if (ai * 4 + m < 7) { const int nx = ai * 4 + m + 1; const bf16_t* np = o0 + (size_t)(row0 + (nx >> 2) * 128 + (nx & 3) * 16) * ldc + col0; qn[0] = *(const u32x4*)np; qn[1] = *(const u32x4*)(np + 128); }
;                     asm volatile("" : "+v"(qc[0]), "+v"(qc[1]));
; #pragma unroll
;                     for (int bj = 0; bj < 2; ++bj) { f32x4 v0 = acc[ai][bj][m][0] + bv[bj][0], v1 = acc[ai][bj][m][1] + bv[bj][1];
;                         const u32x4 q = qc[bj];
;                         v0 = gelu4(v0) * (f32x4){bf_lo(q.x), bf_hi(q.x), bf_lo(q.y), bf_hi(q.y)}; v1 = gelu4(v1) * (f32x4){bf_lo(q.z), bf_hi(q.z), bf_lo(q.w), bf_hi(q.w)};
;                         *(u32x4*)(rowp + bj * 128) = pack8(v0, v1); }
;                     qc[0] = qn[0]; qc[1] = qn[1]; }
	v_mov_b64_e32 v[158:159], v[204:205]
	v_mov_b64_e32 v[160:161], v[206:207]
	v_mov_b64_e32 v[146:147], v[242:243]
	v_mov_b64_e32 v[148:149], v[244:245]
	v_pk_mul_f32 v[190:191], v[190:191], s[16:17] op_sel_hi:[1,0]
	v_add_f32_e32 v0, 1.0, v0
	v_rcp_f32_e32 v192, v0
	v_mul_f32_e32 v0, 0xbfb8aa3b, v193
	v_exp_f32_e32 v0, v0
	s_nop 0
	v_pk_add_f32 v[188:189], v[30:31], v[138:139]
	v_pk_add_f32 v[186:187], v[32:33], v[140:141]
	v_add_f32_e32 v0, 1.0, v0
	v_rcp_f32_e32 v193, v0
	v_mul_f32_e32 v0, 0xbfb8aa3b, v190
	v_exp_f32_e32 v0, v0
	v_pk_add_f32 v[142:143], v[22:23], v[142:143]
	v_pk_mul_f32 v[184:185], v[184:185], v[192:193]
	v_pk_add_f32 v[144:145], v[24:25], v[144:145]
	v_add_f32_e32 v0, 1.0, v0
	v_rcp_f32_e32 v190, v0
	v_mul_f32_e32 v0, 0xbfb8aa3b, v191
	v_exp_f32_e32 v0, v0
	v_pk_add_f32 v[138:139], v[14:15], v[138:139]
	v_pk_add_f32 v[140:141], v[16:17], v[140:141]
	v_add_f32_e32 v0, 1.0, v0
	v_rcp_f32_e32 v191, v0
	s_nop 0
	v_pk_mul_f32 v[182:183], v[182:183], v[190:191]
	v_lshlrev_b32_e32 v190, 16, v154
	v_and_b32_e32 v191, 0xffff0000, v154
	v_lshlrev_b32_e32 v154, 16, v155
	v_and_b32_e32 v155, 0xffff0000, v155
	v_pk_mul_f32 v[182:183], v[182:183], v[154:155]
	v_pk_mul_f32 v[154:155], v[184:185], v[190:191]
	v_pk_mul_f32 v[190:191], v[188:189], v[188:189]
	v_pk_mul_f32 v[184:185], v[186:187], v[186:187]
	v_pk_mul_f32 v[190:191], v[188:189], v[190:191]
	v_pk_mul_f32 v[184:185], v[186:187], v[184:185]
	v_pk_fma_f32 v[190:191], v[190:191], s[14:15], v[188:189] op_sel_hi:[1,0,1]
	v_pk_fma_f32 v[184:185], v[184:185], s[14:15], v[186:187] op_sel_hi:[1,0,1]
	v_pk_mul_f32 v[190:191], v[190:191], s[16:17] op_sel_hi:[1,0]
	v_pk_mul_f32 v[184:185], v[184:185], s[16:17] op_sel_hi:[1,0]
	v_mul_f32_e32 v0, 0xbfb8aa3b, v190
	v_exp_f32_e32 v0, v0
	v_cvt_pk_bf16_f32 v154, v154, v155
	v_cvt_pk_bf16_f32 v155, v182, v183
	v_pk_add_f32 v[182:183], v[12:13], v[132:133]
	v_add_f32_e32 v0, 1.0, v0
	v_rcp_f32_e32 v190, v0
	v_mul_f32_e32 v0, 0xbfb8aa3b, v191
	v_exp_f32_e32 v0, v0
	v_pk_add_f32 v[132:133], v[4:5], v[132:133]
	v_add_f32_e32 v0, 1.0, v0
	v_rcp_f32_e32 v191, v0
	v_mul_f32_e32 v0, 0xbfb8aa3b, v184
	v_exp_f32_e32 v0, v0
	s_nop 0
	v_add_f32_e32 v0, 1.0, v0
	v_rcp_f32_e32 v184, v0
	v_mul_f32_e32 v0, 0xbfb8aa3b, v185
	v_exp_f32_e32 v0, v0
	s_nop 0
	v_add_f32_e32 v0, 1.0, v0
	v_rcp_f32_e32 v185, v0
	s_nop 0
	v_pk_mul_f32 v[184:185], v[186:187], v[184:185]
	v_pk_mul_f32 v[186:187], v[188:189], v[190:191]
	v_lshlrev_b32_e32 v188, 16, v156
	v_and_b32_e32 v189, 0xffff0000, v156
	v_lshlrev_b32_e32 v156, 16, v157
	v_and_b32_e32 v157, 0xffff0000, v157
	v_pk_mul_f32 v[184:185], v[184:185], v[156:157]
	v_pk_mul_f32 v[156:157], v[186:187], v[188:189]
	s_nop 0
	v_cvt_pk_bf16_f32 v156, v156, v157
	v_cvt_pk_bf16_f32 v157, v184, v185
	global_store_dwordx4 v[164:165], v[154:157], off
	v_pk_add_f32 v[184:185], v[10:11], v[130:131]
	v_pk_add_f32 v[130:131], v[2:3], v[130:131]
	v_pk_add_f32 v[156:157], v[18:19], v[134:135]
	v_pk_add_f32 v[154:155], v[20:21], v[136:137]
	v_pk_mul_f32 v[188:189], v[156:157], v[156:157]
	v_pk_mul_f32 v[186:187], v[154:155], v[154:155]
	v_pk_mul_f32 v[188:189], v[156:157], v[188:189]
	v_pk_mul_f32 v[186:187], v[154:155], v[186:187]
	v_pk_fma_f32 v[188:189], v[188:189], s[14:15], v[156:157] op_sel_hi:[1,0,1]
	v_pk_fma_f32 v[186:187], v[186:187], s[14:15], v[154:155] op_sel_hi:[1,0,1]
	v_pk_mul_f32 v[188:189], v[188:189], s[16:17] op_sel_hi:[1,0]
	v_pk_mul_f32 v[186:187], v[186:187], s[16:17] op_sel_hi:[1,0]
	v_mul_f32_e32 v0, 0xbfb8aa3b, v188
	v_exp_f32_e32 v0, v0
	v_pk_add_f32 v[134:135], v[6:7], v[134:135]
	v_pk_add_f32 v[136:137], v[8:9], v[136:137]
	v_add_f32_e32 v0, 1.0, v0
	v_rcp_f32_e32 v188, v0
	v_mul_f32_e32 v0, 0xbfb8aa3b, v189
	v_exp_f32_e32 v0, v0
	s_nop 0
	v_add_f32_e32 v0, 1.0, v0
	v_rcp_f32_e32 v189, v0
	v_mul_f32_e32 v0, 0xbfb8aa3b, v186
	v_exp_f32_e32 v0, v0
	v_pk_mul_f32 v[156:157], v[156:157], v[188:189]
	v_add_f32_e32 v0, 1.0, v0
	v_rcp_f32_e32 v186, v0
	v_mul_f32_e32 v0, 0xbfb8aa3b, v187
	v_exp_f32_e32 v0, v0
	s_nop 0
	v_add_f32_e32 v0, 1.0, v0
	v_rcp_f32_e32 v187, v0
	s_nop 0
	v_pk_mul_f32 v[154:155], v[154:155], v[186:187]
	v_lshlrev_b32_e32 v186, 16, v150
	v_and_b32_e32 v187, 0xffff0000, v150
	v_lshlrev_b32_e32 v150, 16, v151
	v_and_b32_e32 v151, 0xffff0000, v151
	v_pk_mul_f32 v[154:155], v[154:155], v[150:151]
	v_pk_mul_f32 v[150:151], v[156:157], v[186:187]
	v_pk_mul_f32 v[186:187], v[184:185], v[184:185]
	v_pk_mul_f32 v[156:157], v[182:183], v[182:183]
	v_pk_mul_f32 v[186:187], v[184:185], v[186:187]
	v_pk_mul_f32 v[156:157], v[182:183], v[156:157]
	v_pk_fma_f32 v[186:187], v[186:187], s[14:15], v[184:185] op_sel_hi:[1,0,1]
	v_pk_fma_f32 v[156:157], v[156:157], s[14:15], v[182:183] op_sel_hi:[1,0,1]
	v_pk_mul_f32 v[186:187], v[186:187], s[16:17] op_sel_hi:[1,0]
	v_pk_mul_f32 v[156:157], v[156:157], s[16:17] op_sel_hi:[1,0]
	v_mul_f32_e32 v0, 0xbfb8aa3b, v186
	v_exp_f32_e32 v0, v0
	v_cvt_pk_bf16_f32 v150, v150, v151
	v_cvt_pk_bf16_f32 v151, v154, v155
	s_nop 0
	v_add_f32_e32 v0, 1.0, v0
	v_rcp_f32_e32 v186, v0
	v_mul_f32_e32 v0, 0xbfb8aa3b, v187
	v_exp_f32_e32 v0, v0
	s_nop 0
	v_add_f32_e32 v0, 1.0, v0
	v_rcp_f32_e32 v187, v0
	v_mul_f32_e32 v0, 0xbfb8aa3b, v156
	v_exp_f32_e32 v0, v0
	s_nop 0
	v_add_f32_e32 v0, 1.0, v0
	v_rcp_f32_e32 v156, v0
	v_mul_f32_e32 v0, 0xbfb8aa3b, v157
	v_exp_f32_e32 v0, v0
	s_nop 0
	v_add_f32_e32 v0, 1.0, v0
	v_rcp_f32_e32 v157, v0
	s_nop 0
	v_pk_mul_f32 v[156:157], v[182:183], v[156:157]
	v_pk_mul_f32 v[182:183], v[184:185], v[186:187]
	v_lshlrev_b32_e32 v184, 16, v152
	v_and_b32_e32 v185, 0xffff0000, v152
	v_lshlrev_b32_e32 v152, 16, v153
	v_and_b32_e32 v153, 0xffff0000, v153
; __device__ __forceinline__ f32x4 gelu4(const f32x4 x) { const f32x4 u = (x + x * x * x * 0.044715f) * 1.5957691216f; return x * sigmoid4(u); }
; __device__ __forceinline__ float bf_lo(unsigned w) { return __uint_as_float(w << 16); }
; __device__ __forceinline__ float bf_hi(unsigned w) { return __uint_as_float(w & 0xffff0000u); }
; __device__ __forceinline__ u32x4 pack8(const f32x4 a, const f32x4 b) { u32x4 w; w.x = cvt_pk_bf16(a[0], a[1]); w.y = cvt_pk_bf16(a[2], a[3]); w.z = cvt_pk_bf16(b[0], b[1]); w.w = cvt_pk_bf16(b[2], b[3]); return w; }
;     __device__ __forceinline__ void operator()(const f32x4 (&acc)[2][2][4][2], const pg8::Unit& u_in, int wr, int wc, int fr, int fq) const {
;     ...
;             for (int ai = 0; ai < 2; ++ai)
; #pragma unroll
;                 for (int m = 0; m < 4; ++m) { bf16_t* rowp = o0 + (size_t)(row0 + ai * 128 + m * 16) * ldc + col0;
;                     if (ai * 4 + m < 7) { const int nx = ai * 4 + m + 1; const bf16_t* np = o0 + (size_t)(row0 + (nx >> 2) * 128 + (nx & 3) * 16) * ldc + col0; qn[0] = *(const u32x4*)np; qn[1] = *(const u32x4*)(np + 128); }
;                     asm volatile("" : "+v"(qc[0]), "+v"(qc[1]));
; #pragma unroll
;                     for (int bj = 0; bj < 2; ++bj) { f32x4 v0 = acc[ai][bj][m][0] + bv[bj][0], v1 = acc[ai][bj][m][1] + bv[bj][1];
;                         const u32x4 q = qc[bj];
;                         v0 = gelu4(v0) * (f32x4){bf_lo(q.x), bf_hi(q.x), bf_lo(q.y), bf_hi(q.y)}; v1 = gelu4(v1) * (f32x4){bf_lo(q.z), bf_hi(q.z), bf_lo(q.w), bf_hi(q.w)};
;                         *(u32x4*)(rowp + bj * 128) = pack8(v0, v1); }
;                     qc[0] = qn[0]; qc[1] = qn[1]; }
	v_pk_mul_f32 v[156:157], v[156:157], v[152:153]
	v_pk_mul_f32 v[152:153], v[182:183], v[184:185]
	s_nop 0
	v_cvt_pk_bf16_f32 v152, v152, v153
	v_cvt_pk_bf16_f32 v153, v156, v157
	global_store_dwordx4 v[164:165], v[150:153], off offset:256
	s_nop 0
	s_nop 0
	v_pk_mul_f32 v[152:153], v[142:143], v[142:143]
	v_pk_mul_f32 v[150:151], v[144:145], v[144:145]
	v_pk_mul_f32 v[152:153], v[142:143], v[152:153]
	v_pk_mul_f32 v[150:151], v[144:145], v[150:151]
	v_pk_fma_f32 v[152:153], v[152:153], s[14:15], v[142:143] op_sel_hi:[1,0,1]
	v_pk_fma_f32 v[150:151], v[150:151], s[14:15], v[144:145] op_sel_hi:[1,0,1]
	v_pk_mul_f32 v[152:153], v[152:153], s[16:17] op_sel_hi:[1,0]
	v_pk_mul_f32 v[150:151], v[150:151], s[16:17] op_sel_hi:[1,0]
	v_mul_f32_e32 v0, 0xbfb8aa3b, v152
	v_exp_f32_e32 v0, v0
	s_nop 0
	v_add_f32_e32 v0, 1.0, v0
	v_rcp_f32_e32 v152, v0
	v_mul_f32_e32 v0, 0xbfb8aa3b, v153
	v_exp_f32_e32 v0, v0
	s_nop 0
	v_add_f32_e32 v0, 1.0, v0
	v_rcp_f32_e32 v153, v0
	v_mul_f32_e32 v0, 0xbfb8aa3b, v150
	v_exp_f32_e32 v0, v0
	v_pk_mul_f32 v[142:143], v[142:143], v[152:153]
	v_lshlrev_b32_e32 v152, 16, v159
	v_add_f32_e32 v0, 1.0, v0
	v_rcp_f32_e32 v150, v0
	v_mul_f32_e32 v0, 0xbfb8aa3b, v151
	v_exp_f32_e32 v0, v0
	v_and_b32_e32 v153, 0xffff0000, v159
	v_add_f32_e32 v0, 1.0, v0
	v_rcp_f32_e32 v151, v0
	s_nop 0
	v_pk_mul_f32 v[144:145], v[144:145], v[150:151]
	s_nop 0
	v_pk_mul_f32 v[144:145], v[144:145], v[152:153]
	v_pk_mul_f32 v[152:153], v[138:139], v[138:139]
	v_lshlrev_b32_e32 v150, 16, v158
	v_pk_mul_f32 v[152:153], v[138:139], v[152:153]
	v_and_b32_e32 v151, 0xffff0000, v158
	v_pk_fma_f32 v[152:153], v[152:153], s[14:15], v[138:139] op_sel_hi:[1,0,1]
	v_pk_mul_f32 v[142:143], v[142:143], v[150:151]
	v_pk_mul_f32 v[152:153], v[152:153], s[16:17] op_sel_hi:[1,0]
	v_pk_mul_f32 v[150:151], v[140:141], v[140:141]
	v_mul_f32_e32 v0, 0xbfb8aa3b, v152
	v_exp_f32_e32 v0, v0
	v_pk_mul_f32 v[150:151], v[140:141], v[150:151]
	v_add_f32_e32 v0, 1.0, v0
	v_rcp_f32_e32 v152, v0
	v_mul_f32_e32 v0, 0xbfb8aa3b, v153
	v_exp_f32_e32 v0, v0
	v_pk_fma_f32 v[150:151], v[150:151], s[14:15], v[140:141] op_sel_hi:[1,0,1]
	v_add_f32_e32 v0, 1.0, v0
	v_pk_mul_f32 v[150:151], v[150:151], s[16:17] op_sel_hi:[1,0]
	v_rcp_f32_e32 v153, v0
	v_mul_f32_e32 v0, 0xbfb8aa3b, v150
	v_exp_f32_e32 v0, v0
	v_pk_mul_f32 v[138:139], v[138:139], v[152:153]
	v_lshlrev_b32_e32 v152, 16, v161
	v_add_f32_e32 v0, 1.0, v0
	v_rcp_f32_e32 v150, v0
	v_mul_f32_e32 v0, 0xbfb8aa3b, v151
	v_exp_f32_e32 v0, v0
	v_and_b32_e32 v153, 0xffff0000, v161
	v_add_f32_e32 v0, 1.0, v0
	v_rcp_f32_e32 v151, v0
	s_nop 0
	v_pk_mul_f32 v[140:141], v[140:141], v[150:151]
	v_lshlrev_b32_e32 v150, 16, v160
	v_and_b32_e32 v151, 0xffff0000, v160
	v_pk_mul_f32 v[152:153], v[140:141], v[152:153]
	v_pk_mul_f32 v[140:141], v[138:139], v[150:151]
	v_cvt_pk_bf16_f32 v138, v142, v143
	v_cvt_pk_bf16_f32 v139, v144, v145
	s_nop 0
	v_cvt_pk_bf16_f32 v140, v140, v141
	v_cvt_pk_bf16_f32 v141, v152, v153
	global_store_dwordx4 v[162:163], v[138:141], off
	s_nop 1
	v_pk_mul_f32 v[140:141], v[134:135], v[134:135]
	v_pk_mul_f32 v[138:139], v[136:137], v[136:137]
	v_pk_mul_f32 v[140:141], v[134:135], v[140:141]
	v_pk_mul_f32 v[138:139], v[136:137], v[138:139]
	v_pk_fma_f32 v[140:141], v[140:141], s[14:15], v[134:135] op_sel_hi:[1,0,1]
	v_pk_fma_f32 v[138:139], v[138:139], s[14:15], v[136:137] op_sel_hi:[1,0,1]
	v_pk_mul_f32 v[140:141], v[140:141], s[16:17] op_sel_hi:[1,0]
	v_pk_mul_f32 v[138:139], v[138:139], s[16:17] op_sel_hi:[1,0]
	v_mul_f32_e32 v0, 0xbfb8aa3b, v140
	v_exp_f32_e32 v0, v0
	s_nop 0
	v_add_f32_e32 v0, 1.0, v0
	v_rcp_f32_e32 v140, v0
	v_mul_f32_e32 v0, 0xbfb8aa3b, v141
	v_exp_f32_e32 v0, v0
	s_nop 0
	v_add_f32_e32 v0, 1.0, v0
	v_rcp_f32_e32 v141, v0
	v_mul_f32_e32 v0, 0xbfb8aa3b, v138
	v_exp_f32_e32 v0, v0
	v_pk_mul_f32 v[134:135], v[134:135], v[140:141]
	v_lshlrev_b32_e32 v140, 16, v147
	v_add_f32_e32 v0, 1.0, v0
	v_rcp_f32_e32 v138, v0
	v_mul_f32_e32 v0, 0xbfb8aa3b, v139
	v_exp_f32_e32 v0, v0
	v_and_b32_e32 v141, 0xffff0000, v147
	v_add_f32_e32 v0, 1.0, v0
	v_rcp_f32_e32 v139, v0
	s_nop 0
	v_pk_mul_f32 v[136:137], v[136:137], v[138:139]
	s_nop 0
	v_pk_mul_f32 v[136:137], v[136:137], v[140:141]
	v_pk_mul_f32 v[140:141], v[130:131], v[130:131]
	v_lshlrev_b32_e32 v138, 16, v146
	v_pk_mul_f32 v[140:141], v[130:131], v[140:141]
	v_and_b32_e32 v139, 0xffff0000, v146
	v_pk_fma_f32 v[140:141], v[140:141], s[14:15], v[130:131] op_sel_hi:[1,0,1]
	v_pk_mul_f32 v[134:135], v[134:135], v[138:139]
	v_pk_mul_f32 v[140:141], v[140:141], s[16:17] op_sel_hi:[1,0]
	v_pk_mul_f32 v[138:139], v[132:133], v[132:133]
	v_mul_f32_e32 v0, 0xbfb8aa3b, v140
	v_exp_f32_e32 v0, v0
	v_pk_mul_f32 v[138:139], v[132:133], v[138:139]
	v_add_f32_e32 v0, 1.0, v0
	v_rcp_f32_e32 v140, v0
	v_mul_f32_e32 v0, 0xbfb8aa3b, v141
	v_exp_f32_e32 v0, v0
	v_pk_fma_f32 v[138:139], v[138:139], s[14:15], v[132:133] op_sel_hi:[1,0,1]
	v_add_f32_e32 v0, 1.0, v0
	v_pk_mul_f32 v[138:139], v[138:139], s[16:17] op_sel_hi:[1,0]
	v_rcp_f32_e32 v141, v0
	v_mul_f32_e32 v0, 0xbfb8aa3b, v138
	v_exp_f32_e32 v0, v0
	v_pk_mul_f32 v[130:131], v[130:131], v[140:141]
	v_lshlrev_b32_e32 v140, 16, v149
	v_add_f32_e32 v0, 1.0, v0
	v_rcp_f32_e32 v138, v0
	v_mul_f32_e32 v0, 0xbfb8aa3b, v139
	v_exp_f32_e32 v0, v0
	v_and_b32_e32 v141, 0xffff0000, v149
	v_add_f32_e32 v0, 1.0, v0
	v_rcp_f32_e32 v139, v0
	s_nop 0
	v_pk_mul_f32 v[132:133], v[132:133], v[138:139]
	v_lshlrev_b32_e32 v138, 16, v148
	v_and_b32_e32 v139, 0xffff0000, v148
	v_pk_mul_f32 v[140:141], v[132:133], v[140:141]
	v_pk_mul_f32 v[132:133], v[130:131], v[138:139]
	v_cvt_pk_bf16_f32 v130, v134, v135
	v_cvt_pk_bf16_f32 v131, v136, v137
	s_nop 0
	v_cvt_pk_bf16_f32 v132, v132, v133
	v_cvt_pk_bf16_f32 v133, v140, v141
	global_store_dwordx4 v[162:163], v[130:133], off offset:256
